# v11 plus: dropped the store-drain vmcnt(0) at the start of each attention item (no loads pending there)
# speedup vs baseline: 1.0205x; 1.0019x over previous
; DI int my_tid() { int t = threadIdx.x; asm volatile("" : "+v"(t)); return t; }
; DI float bf_lo(unsigned u) { return __uint_as_float(u << 16); }
; DI float bf_hi(unsigned u) { return __uint_as_float(u & 0xffff0000u); }
; DI float rsqrt_f(float x) { return __builtin_amdgcn_rsqf(x); }
; DI void mla_item(PRef p, int j, int seq, int head, int qb, char* smem) {
;   const int tid = my_tid(), lane = tid & 63, w = tid >> 6, r = lane & 31, h = lane >> 5;
;   const int s0 = seq == 0 ? 0 : TP + (seq - 1) * SS;
;   const int S = seq == 0 ? TP : SS;
;   const int pos = qb * 256 + w * 32 + r;
;   const int tok = s0 + pos;
;   const short* Q = (const short*)(p.ws + OFF_Q);
;   const float* gq = p.in[10] + j * 96;
;   float qv[6][8];
;   float ss = 0.f;
; #pragma unroll
;   for (int ks = 0; ks < 6; ks++) {
;     u32x4 t = *(const u32x4*)(Q + (size_t)tok * 1152 + head * 96 + ks * 16 + 8 * h);
; #pragma unroll
;     for (int e = 0; e < 4; e++) {
;       qv[ks][2 * e] = bf_lo(t[e]);
;       qv[ks][2 * e + 1] = bf_hi(t[e]);
;     }
; #pragma unroll
;     for (int e = 0; e < 8; e++) ss += qv[ks][e] * qv[ks][e];
;   }
;   ss += __shfl_xor(ss, 32);
;   const float f = rsqrt_f(ss * (1.f / 96.f) + EPS);
;   const float sc = 0.10206207261596575f * LOG2E;
; #pragma unroll
;   for (int ks = 0; ks < 6; ks++)
; #pragma unroll
;     for (int e = 0; e < 8; e++) qv[ks][e] *= f * gq[ks * 16 + 8 * h + e];
; #pragma unroll
;   for (int e = 0; e < 8; e++) {
;     float cs, sn;
;     rope_cs(pos, 8 * h + e, cs, sn);
.LBB0_165:
	v_mov_b32_e32 v10, v196
	s_getpc_b64 s[8:9]
	s_add_u32 s8, s8, _ZL10ROPE_TURNS@rel32@lo+4
	s_addc_u32 s9, s9, _ZL10ROPE_TURNS@rel32@hi+12
	v_lshrrev_b32_e32 v0, 2, v10
	v_and_b32_e32 v11, 8, v0
	v_lshlrev_b32_e32 v4, 3, v11
	global_load_dwordx4 v[0:3], v4, s[8:9]
	global_load_dwordx4 v[18:21], v4, s[8:9] offset:16
	global_load_dwordx4 v[22:25], v4, s[8:9] offset:32
	global_load_dwordx4 v[6:9], v4, s[8:9] offset:48
	s_ashr_i32 s8, s20, 2
	s_and_b32 s9, s20, 31
	s_and_b32 s8, s8, -8
	v_readlane_b32 s16, v226, 15
	v_ashrrev_i32_e32 v12, 1, v10
	s_or_b32 s9, s9, s16
	s_or_b32 s8, s8, s52
	v_and_b32_e32 v12, 0xffffffe0, v12
	s_ashr_i32 s16, s8, 1
	v_lshl_add_u32 v12, s9, 8, v12
	v_mov_b64_e32 v[4:5], s[4:5]
	s_mul_i32 s8, s16, 0x60
	v_and_or_b32 v102, v10, 31, v12
	s_movk_i32 s21, 0x900
	s_ashr_i32 s9, s8, 31
	v_mad_i64_i32 v[4:5], s[22:23], v102, s21, v[4:5]
	s_waitcnt vmcnt(11)
	v_lshlrev_b32_e32 v128, 1, v11
	v_lshl_add_u64 v[4:5], s[8:9], 1, v[4:5]
	v_lshl_add_u64 v[4:5], v[4:5], 0, v[128:129]
	global_load_dwordx4 v[44:47], v[4:5], off offset:128
	global_load_dwordx4 v[52:55], v[4:5], off offset:160
	global_load_dwordx4 v[56:59], v[4:5], off offset:64
	global_load_dwordx4 v[60:63], v[4:5], off offset:96
	v_and_b32_e32 v12, 64, v200
	v_xor_b32_e32 v10, 32, v200
	v_add_u32_e32 v12, 64, v12
	v_cmp_lt_i32_e32 vcc, v10, v12
	v_lshlrev_b32_e32 v128, 2, v11
	v_cvt_f64_i32_e32 v[48:49], v102
	v_cndmask_b32_e32 v10, v200, v10, vcc
	v_lshlrev_b32_e32 v103, 2, v10
	global_load_dwordx4 v[10:13], v[4:5], off
	global_load_dwordx4 v[14:17], v[4:5], off offset:32
	s_mul_i32 s8, s16, 0xf00000
	s_mul_hi_i32 s9, s16, 0xf00000
	s_add_u32 s8, s10, s8
	s_addc_u32 s9, s11, s9
	s_mul_i32 s28, s16, 0xa00000
	s_mul_hi_i32 s29, s16, 0xa00000
	s_add_u32 s28, s12, s28
	s_addc_u32 s29, s13, s29
	s_mov_b32 s37, 0x500000
	s_mov_b32 s30, 0x3e16c740
	s_mov_b32 s23, 2
	s_mov_b32 s22, 1
	s_mov_b32 s21, 0
	s_waitcnt vmcnt(9)
	v_mul_f64 v[4:5], v[0:1], v[48:49]
	v_mul_f64 v[26:27], v[2:3], v[48:49]
	s_waitcnt vmcnt(8)
	v_mul_f64 v[28:29], v[18:19], v[48:49]
	v_mul_f64 v[30:31], v[20:21], v[48:49]
	s_waitcnt vmcnt(7)
	v_mul_f64 v[32:33], v[22:23], v[48:49]
	v_mul_f64 v[34:35], v[24:25], v[48:49]
	s_waitcnt vmcnt(6)
	v_mul_f64 v[36:37], v[6:7], v[48:49]
	v_floor_f64_e32 v[4:5], v[4:5]
	v_floor_f64_e32 v[26:27], v[26:27]
	v_floor_f64_e32 v[28:29], v[28:29]
	v_floor_f64_e32 v[30:31], v[30:31]
	v_floor_f64_e32 v[32:33], v[32:33]
	v_floor_f64_e32 v[34:35], v[34:35]
	v_floor_f64_e32 v[36:37], v[36:37]
	v_fma_f64 v[0:1], v[0:1], v[48:49], -v[4:5]
	v_fma_f64 v[2:3], v[2:3], v[48:49], -v[26:27]
	v_fma_f64 v[4:5], v[18:19], v[48:49], -v[28:29]
	v_fma_f64 v[18:19], v[20:21], v[48:49], -v[30:31]
	v_fma_f64 v[20:21], v[22:23], v[48:49], -v[32:33]
	v_fma_f64 v[22:23], v[24:25], v[48:49], -v[34:35]
	v_fma_f64 v[6:7], v[6:7], v[48:49], -v[36:37]
	v_cvt_f32_f64_e32 v0, v[0:1]
	v_cvt_f32_f64_e32 v1, v[2:3]
	v_cvt_f32_f64_e32 v2, v[4:5]
	v_cvt_f32_f64_e32 v3, v[18:19]
	v_cvt_f32_f64_e32 v4, v[20:21]
	v_cvt_f32_f64_e32 v5, v[22:23]
	v_cvt_f32_f64_e32 v6, v[6:7]
	v_sin_f32_e32 v28, v0
	v_cos_f32_e32 v26, v0
	v_sin_f32_e32 v29, v1
	v_cos_f32_e32 v27, v1
	v_sin_f32_e32 v66, v2
	v_cos_f32_e32 v30, v2
	v_sin_f32_e32 v67, v3
	v_cos_f32_e32 v31, v3
	v_sin_f32_e32 v24, v4
	v_cos_f32_e32 v22, v4
	v_sin_f32_e32 v25, v5
	v_cos_f32_e32 v23, v5
	v_sin_f32_e32 v20, v6
	v_cos_f32_e32 v18, v6
	s_waitcnt vmcnt(5)
	v_lshlrev_b32_e32 v34, 16, v47
	v_and_b32_e32 v35, 0xffff0000, v47
	s_waitcnt vmcnt(4)
	v_lshlrev_b32_e32 v32, 16, v55
	v_and_b32_e32 v33, 0xffff0000, v55
	global_load_dwordx4 v[0:3], v128, s[6:7] offset:272
	global_load_dwordx4 v[4:7], v128, s[6:7] offset:256
	v_lshlrev_b32_e32 v38, 16, v46
	v_and_b32_e32 v39, 0xffff0000, v46
	v_lshlrev_b32_e32 v36, 16, v54
	v_and_b32_e32 v37, 0xffff0000, v54
	v_lshlrev_b32_e32 v42, 16, v45
	v_and_b32_e32 v43, 0xffff0000, v45
	v_lshlrev_b32_e32 v40, 16, v53
	v_and_b32_e32 v41, 0xffff0000, v53
	v_lshlrev_b32_e32 v46, 16, v44
	v_and_b32_e32 v47, 0xffff0000, v44
	v_lshlrev_b32_e32 v44, 16, v52
	v_and_b32_e32 v45, 0xffff0000, v52
	s_waitcnt vmcnt(4)
	v_lshlrev_b32_e32 v104, 16, v63
	v_and_b32_e32 v105, 0xffff0000, v63
	global_load_dwordx4 v[52:55], v128, s[6:7] offset:208
	global_load_dwordx4 v[68:71], v128, s[6:7] offset:192
	v_lshlrev_b32_e32 v108, 16, v62
	v_and_b32_e32 v109, 0xffff0000, v62
	v_lshlrev_b32_e32 v112, 16, v61
	v_and_b32_e32 v113, 0xffff0000, v61
	v_lshlrev_b32_e32 v116, 16, v60
	v_and_b32_e32 v117, 0xffff0000, v60
	v_lshlrev_b32_e32 v120, 16, v59
	v_and_b32_e32 v121, 0xffff0000, v59
	global_load_dwordx4 v[60:63], v128, s[6:7] offset:144
	global_load_dwordx4 v[72:75], v128, s[6:7] offset:128
	v_lshlrev_b32_e32 v124, 16, v58
	v_and_b32_e32 v125, 0xffff0000, v58
	v_lshlrev_b32_e32 v130, 16, v57
	v_and_b32_e32 v131, 0xffff0000, v57
	v_lshlrev_b32_e32 v134, 16, v56
	v_and_b32_e32 v135, 0xffff0000, v56
	global_load_dwordx4 v[56:59], v128, s[6:7] offset:80
	global_load_dwordx4 v[76:79], v128, s[6:7] offset:64
	global_load_dwordx4 v[80:83], v128, s[6:7] offset:16
	global_load_dwordx4 v[84:87], v128, s[6:7]
	s_waitcnt vmcnt(11)
	v_lshlrev_b32_e32 v160, 16, v10
	v_and_b32_e32 v161, 0xffff0000, v10
	v_lshlrev_b32_e32 v156, 16, v11
	v_and_b32_e32 v157, 0xffff0000, v11
	v_pk_mul_f32 v[10:11], v[160:161], v[160:161]
	v_pk_mul_f32 v[158:159], v[156:157], v[156:157]
	v_add_f32_e32 v10, v10, v11
	v_lshlrev_b32_e32 v154, 16, v12
	v_and_b32_e32 v155, 0xffff0000, v12
	v_add_f32_e32 v10, v158, v10
	v_lshlrev_b32_e32 v150, 16, v13
	v_and_b32_e32 v151, 0xffff0000, v13
	v_pk_mul_f32 v[12:13], v[154:155], v[154:155]
	v_add_f32_e32 v10, v159, v10
	v_add_f32_e32 v10, v12, v10
	v_pk_mul_f32 v[152:153], v[150:151], v[150:151]
	v_add_f32_e32 v10, v13, v10
	s_waitcnt vmcnt(10)
; DI float rsqrt_f(float x) { return __builtin_amdgcn_rsqf(x); }
; DI void mla_item(PRef p, int j, int seq, int head, int qb, char* smem) {
;     ...
; #pragma unroll
;     for (int e = 0; e < 8; e++) ss += qv[ks][e] * qv[ks][e];
;   }
;   ss += __shfl_xor(ss, 32);
;   const float f = rsqrt_f(ss * (1.f / 96.f) + EPS);
;   const float sc = 0.10206207261596575f * LOG2E;
; #pragma unroll
;   for (int ks = 0; ks < 6; ks++)
; #pragma unroll
;     for (int e = 0; e < 8; e++) qv[ks][e] *= f * gq[ks * 16 + 8 * h + e];
	v_lshlrev_b32_e32 v148, 16, v14
	v_and_b32_e32 v149, 0xffff0000, v14
	v_add_f32_e32 v10, v152, v10
	v_lshlrev_b32_e32 v144, 16, v15
	v_and_b32_e32 v145, 0xffff0000, v15
	v_pk_mul_f32 v[14:15], v[148:149], v[148:149]
	v_add_f32_e32 v10, v153, v10
	v_add_f32_e32 v10, v14, v10
	v_pk_mul_f32 v[146:147], v[144:145], v[144:145]
	v_add_f32_e32 v10, v15, v10
	v_lshlrev_b32_e32 v142, 16, v16
	v_and_b32_e32 v143, 0xffff0000, v16
	v_add_f32_e32 v10, v146, v10
	v_lshlrev_b32_e32 v138, 16, v17
	v_and_b32_e32 v139, 0xffff0000, v17
	v_pk_mul_f32 v[16:17], v[142:143], v[142:143]
	v_add_f32_e32 v10, v147, v10
	v_add_f32_e32 v10, v16, v10
	v_pk_mul_f32 v[140:141], v[138:139], v[138:139]
	v_add_f32_e32 v10, v17, v10
	v_add_f32_e32 v10, v140, v10
	v_pk_mul_f32 v[136:137], v[134:135], v[134:135]
	v_add_f32_e32 v10, v141, v10
	v_add_f32_e32 v10, v136, v10
	v_pk_mul_f32 v[132:133], v[130:131], v[130:131]
	v_add_f32_e32 v10, v137, v10
	v_add_f32_e32 v10, v132, v10
	v_pk_mul_f32 v[126:127], v[124:125], v[124:125]
	v_add_f32_e32 v10, v133, v10
	v_add_f32_e32 v10, v126, v10
	v_pk_mul_f32 v[122:123], v[120:121], v[120:121]
	v_add_f32_e32 v10, v127, v10
	v_add_f32_e32 v10, v122, v10
	v_pk_mul_f32 v[118:119], v[116:117], v[116:117]
	v_add_f32_e32 v10, v123, v10
	v_add_f32_e32 v10, v118, v10
	v_pk_mul_f32 v[114:115], v[112:113], v[112:113]
	v_add_f32_e32 v10, v119, v10
	v_add_f32_e32 v10, v114, v10
	v_pk_mul_f32 v[110:111], v[108:109], v[108:109]
	v_add_f32_e32 v10, v115, v10
	v_add_f32_e32 v10, v110, v10
	v_pk_mul_f32 v[106:107], v[104:105], v[104:105]
	v_add_f32_e32 v10, v111, v10
	v_add_f32_e32 v10, v106, v10
	v_pk_mul_f32 v[98:99], v[46:47], v[46:47]
	v_add_f32_e32 v10, v107, v10
	v_add_f32_e32 v10, v98, v10
	v_pk_mul_f32 v[94:95], v[42:43], v[42:43]
	v_add_f32_e32 v10, v99, v10
	v_add_f32_e32 v10, v94, v10
	v_pk_mul_f32 v[90:91], v[38:39], v[38:39]
	v_add_f32_e32 v10, v95, v10
	v_add_f32_e32 v10, v90, v10
	v_pk_mul_f32 v[64:65], v[34:35], v[34:35]
	v_add_f32_e32 v10, v91, v10
	v_add_f32_e32 v10, v64, v10
	v_pk_mul_f32 v[100:101], v[44:45], v[44:45]
	v_add_f32_e32 v10, v65, v10
	v_add_f32_e32 v10, v100, v10
	v_pk_mul_f32 v[96:97], v[40:41], v[40:41]
	v_add_f32_e32 v10, v101, v10
	v_add_f32_e32 v10, v96, v10
	v_pk_mul_f32 v[92:93], v[36:37], v[36:37]
	v_add_f32_e32 v10, v97, v10
	v_add_f32_e32 v10, v92, v10
	v_pk_mul_f32 v[88:89], v[32:33], v[32:33]
	v_add_f32_e32 v10, v93, v10
	v_add_f32_e32 v10, v88, v10
	v_add_f32_e32 v12, v89, v10
	ds_bpermute_b32 v13, v103, v12
	v_mul_f64 v[50:51], v[8:9], v[48:49]
	v_floor_f64_e32 v[10:11], v[50:51]
	v_fma_f64 v[8:9], v[8:9], v[48:49], -v[10:11]
	v_cvt_f32_f64_e32 v8, v[8:9]
	s_waitcnt lgkmcnt(0)
	v_add_f32_e32 v9, v12, v13
	v_fmamk_f32 v9, v9, 0x3c2aaaab, v198
	v_rsq_f32_e32 v100, v9
	global_load_dwordx4 v[48:51], v128, s[6:7] offset:336
	global_load_dwordx4 v[88:91], v128, s[6:7] offset:320
	v_sin_f32_e32 v21, v8
	v_cos_f32_e32 v19, v8
	s_waitcnt vmcnt(2)
	v_pk_mul_f32 v[8:9], v[84:85], v[100:101] op_sel_hi:[1,0]
	v_pk_mul_f32 v[10:11], v[52:53], v[100:101] op_sel_hi:[1,0]
	v_pk_mul_f32 v[106:107], v[8:9], v[160:161]
	v_pk_mul_f32 v[8:9], v[86:87], v[100:101] op_sel_hi:[1,0]
	v_mov_b32_e32 v160, v196
	v_pk_mul_f32 v[126:127], v[8:9], v[156:157]
	v_pk_mul_f32 v[8:9], v[80:81], v[100:101] op_sel_hi:[1,0]
	v_pk_mul_f32 v[12:13], v[54:55], v[100:101] op_sel_hi:[1,0]
	v_pk_mul_f32 v[132:133], v[8:9], v[154:155]
	v_pk_mul_f32 v[8:9], v[82:83], v[100:101] op_sel_hi:[1,0]
	v_lshlrev_b32_e32 v52, 4, v160
	v_pk_mul_f32 v[136:137], v[8:9], v[150:151]
	v_pk_mul_f32 v[8:9], v[76:77], v[100:101] op_sel_hi:[1,0]
	v_pk_mul_f32 v[4:5], v[4:5], v[100:101] op_sel_hi:[1,0]
	v_pk_mul_f32 v[140:141], v[8:9], v[148:149]
	v_pk_mul_f32 v[8:9], v[78:79], v[100:101] op_sel_hi:[1,0]
	v_and_b32_e32 v128, 0xf0, v52
	v_pk_mul_f32 v[144:145], v[8:9], v[144:145]
	v_pk_mul_f32 v[8:9], v[56:57], v[100:101] op_sel_hi:[1,0]
	v_mov_b64_e32 v[52:53], s[28:29]
	v_pk_mul_f32 v[56:57], v[8:9], v[142:143]
	v_pk_mul_f32 v[8:9], v[58:59], v[100:101] op_sel_hi:[1,0]
	s_mov_b32 s28, 0x28000
	v_pk_mul_f32 v[58:59], v[8:9], v[138:139]
	v_pk_mul_f32 v[8:9], v[72:73], v[100:101] op_sel_hi:[1,0]
	v_lshlrev_b32_e32 v92, 3, v160
	v_pk_mul_f32 v[134:135], v[8:9], v[134:135]
	v_pk_mul_f32 v[8:9], v[74:75], v[100:101] op_sel_hi:[1,0]
	v_add_u32_e32 v94, 0x1000, v92
	v_pk_mul_f32 v[130:131], v[8:9], v[130:131]
	v_pk_mul_f32 v[8:9], v[60:61], v[100:101] op_sel_hi:[1,0]
	v_add_u32_e32 v96, 0x2000, v92
	v_pk_mul_f32 v[14:15], v[8:9], v[124:125]
	v_pk_mul_f32 v[8:9], v[62:63], v[100:101] op_sel_hi:[1,0]
	v_ashrrev_i32_e32 v93, 31, v92
	v_pk_mul_f32 v[16:17], v[8:9], v[120:121]
	v_pk_mul_f32 v[8:9], v[68:69], v[100:101] op_sel_hi:[1,0]
	v_ashrrev_i32_e32 v95, 31, v94
	v_pk_mul_f32 v[60:61], v[8:9], v[116:117]
	v_pk_mul_f32 v[8:9], v[70:71], v[100:101] op_sel_hi:[1,0]
	v_ashrrev_i32_e32 v101, 4, v160
	v_mad_i64_i32 v[52:53], s[28:29], v101, s28, v[52:53]
	v_ashrrev_i32_e32 v97, 31, v96
	s_add_u32 s28, s8, 0x6000
	v_pk_mul_f32 v[10:11], v[10:11], v[108:109]
	v_pk_mul_f32 v[12:13], v[12:13], v[104:105]
	v_lshlrev_b64 v[54:55], 1, v[92:93]
	v_lshlrev_b64 v[104:105], 1, v[94:95]
	v_lshlrev_b64 v[108:109], 1, v[96:97]
	v_lshl_add_u64 v[98:99], v[52:53], 0, v[128:129]
	s_addc_u32 s29, s9, 0
	v_lshl_add_u64 v[62:63], s[8:9], 0, v[54:55]
	v_lshl_add_u64 v[68:69], s[8:9], 0, v[104:105]
	v_lshl_add_u64 v[76:77], s[8:9], 0, v[108:109]
	v_add_co_u32_e32 v52, vcc, s37, v98
	v_lshl_add_u64 v[54:55], s[28:29], 0, v[54:55]
	global_load_dwordx4 v[62:65], v[62:63], off
	s_nop 0
	global_load_dwordx4 v[68:71], v[68:69], off
	v_addc_co_u32_e32 v53, vcc, 0, v99, vcc
	global_load_dwordx4 v[72:75], v[98:99], off
	s_nop 0
	global_load_dwordx4 v[76:79], v[76:77], off
	s_nop 0
	global_load_dwordx4 v[80:83], v[52:53], off
	global_load_dwordx4 v[84:87], v[54:55], off
	v_lshl_add_u64 v[54:55], s[28:29], 0, v[104:105]
	v_pk_mul_f32 v[8:9], v[8:9], v[112:113]
	v_lshl_add_u64 v[104:105], s[28:29], 0, v[108:109]
	global_load_dwordx4 v[108:111], v[54:55], off
	global_load_dwordx4 v[112:115], v[104:105], off
	global_load_dwordx4 v[116:119], v[98:99], off offset:256
	global_load_dwordx4 v[120:123], v[52:53], off offset:256
	v_pk_mul_f32 v[0:1], v[0:1], v[100:101] op_sel_hi:[1,0]
	v_pk_mul_f32 v[124:125], v[4:5], v[46:47]
	v_pk_mul_f32 v[142:143], v[0:1], v[38:39]
	v_pk_mul_f32 v[0:1], v[2:3], v[100:101] op_sel_hi:[1,0]
	v_pk_mul_f32 v[4:5], v[6:7], v[100:101] op_sel_hi:[1,0]
	v_pk_mul_f32 v[146:147], v[0:1], v[34:35]
	v_pk_mul_f32 v[138:139], v[4:5], v[42:43]
	v_mul_hi_i32 v3, v160, s41
	s_waitcnt vmcnt(10)
; DI void mla_item(PRef p, int j, int seq, int head, int qb, char* smem) {
;     ...
;   for (int e = 0; e < 8; e++) {
;     float cs, sn;
;     rope_cs(pos, 8 * h + e, cs, sn);
;     float x1 = qv[4][e], x2 = qv[5][e];
;     qv[4][e] = x1 * cs - x2 * sn;
;     qv[5][e] = x1 * sn + x2 * cs;
;   }
;   bf16x8 qf[6];
; #pragma unroll
;   for (int ks = 0; ks < 6; ks++) {
;     u32x4 t;
; #pragma unroll
;     for (int e = 0; e < 4; e++) t[e] = pack_bf16(qv[ks][2 * e] * sc, qv[ks][2 * e + 1] * sc);
;     qf[ks] = __builtin_bit_cast(bf16x8, t);
;   }
	v_pk_mul_f32 v[0:1], v[88:89], v[100:101] op_sel_hi:[1,0]
	v_lshrrev_b32_e32 v6, 31, v3
	v_pk_mul_f32 v[88:89], v[0:1], v[44:45]
	v_pk_mul_f32 v[0:1], v[90:91], v[100:101] op_sel_hi:[1,0]
	v_lshrrev_b32_e32 v3, 1, v3
	v_pk_mul_f32 v[90:91], v[0:1], v[40:41]
	v_pk_mul_f32 v[0:1], v[48:49], v[100:101] op_sel_hi:[1,0]
	v_add_u32_e32 v3, v3, v6
	v_pk_mul_f32 v[148:149], v[0:1], v[36:37]
	v_pk_mul_f32 v[0:1], v[50:51], v[100:101] op_sel_hi:[1,0]
	v_add_lshl_u32 v104, v3, v160, 4
	v_pk_mul_f32 v[150:151], v[0:1], v[32:33]
	v_pk_mul_f32 v[0:1], v[88:89], v[26:27]
	v_add_u32_e32 v3, 0x200, v160
	v_pk_fma_f32 v[152:153], v[124:125], v[28:29], v[0:1]
	v_pk_mul_f32 v[0:1], v[90:91], v[30:31]
	v_mul_hi_i32 v6, v3, s41
	v_pk_fma_f32 v[154:155], v[138:139], v[66:67], v[0:1]
	v_pk_mul_f32 v[0:1], v[148:149], v[22:23]
	v_lshrrev_b32_e32 v7, 31, v6
	v_pk_fma_f32 v[156:157], v[142:143], v[24:25], v[0:1]
	v_pk_mul_f32 v[0:1], v[150:151], v[18:19]
	v_lshrrev_b32_e32 v6, 1, v6
	v_pk_fma_f32 v[158:159], v[146:147], v[20:21], v[0:1]
	v_pk_mul_f32 v[0:1], v[106:107], s[30:31] op_sel_hi:[1,0]
	v_add_u32_e32 v6, v6, v7
	v_cvt_pk_bf16_f32 v48, v0, v1
	v_pk_mul_f32 v[0:1], v[126:127], s[30:31] op_sel_hi:[1,0]
	v_add_lshl_u32 v105, v6, v3, 4
	v_cvt_pk_bf16_f32 v49, v0, v1
	v_pk_mul_f32 v[0:1], v[132:133], s[30:31] op_sel_hi:[1,0]
	v_add_u32_e32 v3, 0x400, v160
	v_cvt_pk_bf16_f32 v50, v0, v1
	v_pk_mul_f32 v[0:1], v[136:137], s[30:31] op_sel_hi:[1,0]
	v_mul_hi_i32 v6, v3, s41
	v_cvt_pk_bf16_f32 v51, v0, v1
	v_pk_mul_f32 v[0:1], v[140:141], s[30:31] op_sel_hi:[1,0]
	v_lshrrev_b32_e32 v7, 31, v6
	v_cvt_pk_bf16_f32 v52, v0, v1
	v_pk_mul_f32 v[0:1], v[144:145], s[30:31] op_sel_hi:[1,0]
	v_lshrrev_b32_e32 v6, 1, v6
	v_cvt_pk_bf16_f32 v53, v0, v1
	v_pk_mul_f32 v[0:1], v[56:57], s[30:31] op_sel_hi:[1,0]
	v_add_u32_e32 v6, v6, v7
	v_cvt_pk_bf16_f32 v54, v0, v1
	v_pk_mul_f32 v[0:1], v[58:59], s[30:31] op_sel_hi:[1,0]
	v_add_lshl_u32 v106, v6, v3, 4
	v_cvt_pk_bf16_f32 v55, v0, v1
	v_pk_mul_f32 v[0:1], v[134:135], s[30:31] op_sel_hi:[1,0]
	v_and_b32_e32 v3, 19, v160
	v_cvt_pk_bf16_f32 v56, v0, v1
	v_lshlrev_b32_e32 v0, 1, v160
	v_lshrrev_b32_e32 v1, 1, v160
	v_and_b32_e32 v0, 8, v0
	v_and_b32_e32 v2, 4, v1
	v_and_b32_e32 v126, 16, v1
	v_or3_b32 v0, v3, v0, v2
	s_movk_i32 s28, 0xd0
	v_mad_u32_u24 v107, v0, s28, v126
	v_mad_u64_u32 v[100:101], s[28:29], v101, s36, v[128:129]
	v_add_u32_e32 v0, 0x6800, v100
	s_waitcnt vmcnt(9)
	ds_write_b128 v104, v[62:65]
	s_waitcnt vmcnt(8)
	ds_write_b128 v105, v[68:71]
	s_waitcnt vmcnt(6)
	ds_write_b128 v106, v[76:79]
	ds_write_b128 v100, v[72:75] offset:26624
	s_waitcnt vmcnt(5)
	ds_write_b128 v100, v[80:83] offset:35328
	s_waitcnt vmcnt(4)
	ds_write_b128 v104, v[84:87] offset:44032
	s_waitcnt vmcnt(3)
	ds_write_b128 v105, v[108:111] offset:44032
	s_waitcnt vmcnt(2)
	ds_write_b128 v106, v[112:115] offset:44032
	s_waitcnt vmcnt(1)
	ds_write_b128 v0, v[116:119] offset:44032
	s_waitcnt vmcnt(0)
	ds_write_b128 v0, v[120:123] offset:52736
	s_waitcnt lgkmcnt(0)
	s_barrier
; #define KLOAD(kf_, base)                                                                       \
;   { _Pragma("unroll") for (int ks = 0; ks < NKS; ks++) kf_[ks] = *(const bf16x8*)((base) + kfo + ks * 32); }
; #define QKM(dst, kf_)                                                                          \
;   {                                                                                            \
;     _Pragma("unroll") for (int i = 0; i < 16; i++) dst[i] = 0.f;                               \
;     _Pragma("unroll") for (int ks = 0; ks < NKS; ks++) dst = MFMA(kf_[ks], qf[ks], dst);       \
;   }
; template <int DK>
; DI void attn_core(const bf16x8 (&qf)[DK / 16], const short* Kg, const short* VTg, size_t ldvt, int ntiles, char* smem,
;                   f32x16 (&O)[2], float& lsum) {
;     ...
;   f32x16 Sc;
;   {
;     bf16x8 kf[NKS];
;     KLOAD(kf, smem);
;     QKM(Sc, kf);
;   }
; DI void mla_item(PRef p, int j, int seq, int head, int qb, char* smem) {
;     ...
;   bf16x8 qf[6];
; #pragma unroll
;   for (int ks = 0; ks < 6; ks++) {
;     u32x4 t;
; #pragma unroll
;     for (int e = 0; e < 4; e++) t[e] = pack_bf16(qv[ks][2 * e] * sc, qv[ks][2 * e + 1] * sc);
;     qf[ks] = __builtin_bit_cast(bf16x8, t);
;   }
	ds_read_b128 v[0:3], v107
	v_pk_mul_f32 v[4:5], v[130:131], s[30:31] op_sel_hi:[1,0]
	v_mov_b32_e32 v108, 0
	v_cvt_pk_bf16_f32 v57, v4, v5
	v_pk_mul_f32 v[4:5], v[14:15], s[30:31] op_sel_hi:[1,0]
	s_mov_b32 s28, 0
	v_cvt_pk_bf16_f32 v58, v4, v5
	v_pk_mul_f32 v[4:5], v[16:17], s[30:31] op_sel_hi:[1,0]
	v_mov_b32_e32 v14, v108
	v_cvt_pk_bf16_f32 v59, v4, v5
	v_pk_mul_f32 v[4:5], v[60:61], s[30:31] op_sel_hi:[1,0]
	v_mov_b32_e32 v15, v108
	v_cvt_pk_bf16_f32 v60, v4, v5
	ds_read_b128 v[4:7], v107 offset:32
	s_waitcnt lgkmcnt(1)
	v_mfma_f32_32x32x16_bf16 v[32:47], v[0:3], v[48:51], 0
	v_mul_f32_e64 v0, v8, s30
	v_mul_f32_e64 v1, v9, s30
	v_mov_b32_e32 v16, 0
	v_cvt_pk_bf16_f32 v61, v0, v1
	v_mul_f32_e64 v0, v10, s30
	v_mul_f32_e64 v1, v11, s30
	v_mov_b32_e32 v10, v108
	v_cvt_pk_bf16_f32 v62, v0, v1
	v_pk_mul_f32 v[0:1], v[12:13], s[30:31] op_sel_hi:[1,0]
	s_waitcnt lgkmcnt(0)
	v_mfma_f32_32x32x16_bf16 v[32:47], v[4:7], v[52:55], v[32:47]
	v_cvt_pk_bf16_f32 v63, v0, v1
	ds_read_b128 v[0:3], v107 offset:64
	v_mul_f32_e64 v4, v88, v28
	v_mul_f32_e64 v5, v89, v29
	v_mov_b32_e32 v11, v108
	v_pk_fma_f32 v[4:5], v[124:125], v[26:27], v[4:5] neg_lo:[0,0,1] neg_hi:[0,0,1]
	v_mov_b32_e32 v12, v108
	v_pk_mul_f32 v[4:5], v[4:5], s[30:31] op_sel_hi:[1,0]
	v_mov_b32_e32 v13, v108
	v_cvt_pk_bf16_f32 v64, v4, v5
	v_pk_mul_f32 v[4:5], v[90:91], v[66:67]
	v_mov_b32_e32 v17, v108
	v_pk_fma_f32 v[8:9], v[138:139], v[30:31], v[4:5] neg_lo:[0,0,1] neg_hi:[0,0,1]
	ds_read_b128 v[4:7], v107 offset:96
	s_waitcnt lgkmcnt(1)
	v_mfma_f32_32x32x16_bf16 v[32:47], v[0:3], v[56:59], v[32:47]
	v_mul_f32_e64 v0, v8, s30
	v_mul_f32_e64 v1, v9, s30
	v_mov_b32_e32 v8, v108
	v_cvt_pk_bf16_f32 v65, v0, v1
	v_mul_f32_e64 v0, v148, v24
	v_mul_f32_e64 v1, v149, v25
	v_mov_b32_e32 v9, v108
	v_pk_fma_f32 v[0:1], v[142:143], v[22:23], v[0:1] neg_lo:[0,0,1] neg_hi:[0,0,1]
	v_mov_b32_e32 v22, v108
	v_pk_mul_f32 v[0:1], v[0:1], s[30:31] op_sel_hi:[1,0]
	s_waitcnt lgkmcnt(0)
	v_mfma_f32_32x32x16_bf16 v[32:47], v[4:7], v[60:63], v[32:47]
	v_cvt_pk_bf16_f32 v66, v0, v1
	ds_read_b128 v[0:3], v107 offset:128
	v_mul_f32_e64 v4, v150, v20
	v_mul_f32_e64 v5, v151, v21
	v_mov_b32_e32 v20, v108
	v_pk_fma_f32 v[4:5], v[146:147], v[18:19], v[4:5] neg_lo:[0,0,1] neg_hi:[0,0,1]
	v_mov_b32_e32 v18, v108
	v_pk_mul_f32 v[4:5], v[4:5], s[30:31] op_sel_hi:[1,0]
	v_mov_b32_e32 v19, v108
	v_cvt_pk_bf16_f32 v67, v4, v5
	v_pk_mul_f32 v[4:5], v[152:153], s[30:31] op_sel_hi:[1,0]
	v_mov_b32_e32 v21, v108
	v_cvt_pk_bf16_f32 v68, v4, v5
	ds_read_b128 v[4:7], v107 offset:160
	s_waitcnt lgkmcnt(1)
	v_mfma_f32_32x32x16_bf16 v[32:47], v[0:3], v[64:67], v[32:47]
	v_mul_f32_e64 v0, v154, s30
	v_mul_f32_e64 v1, v155, s30
	v_mov_b32_e32 v2, v108
	v_cvt_pk_bf16_f32 v69, v0, v1
	v_mul_f32_e64 v0, v156, s30
	v_mul_f32_e64 v1, v157, s30
	v_mov_b32_e32 v3, v108
	v_cvt_pk_bf16_f32 v70, v0, v1
	v_pk_mul_f32 v[0:1], v[158:159], s[30:31] op_sel_hi:[1,0]
	v_mov_b32_e32 v23, v108
	v_cvt_pk_bf16_f32 v71, v0, v1
	v_and_b32_e32 v0, 31, v160
	v_mad_u32_u24 v101, v0, s36, v126
	s_waitcnt lgkmcnt(0)
	v_mfma_f32_32x32x16_bf16 v[32:47], v[4:7], v[68:71], v[32:47]
	v_mov_b32_e32 v0, 0
	v_mov_b32_e32 v1, v108
	v_mov_b32_e32 v4, v108
	v_mov_b32_e32 v5, v108
	v_mov_b32_e32 v6, v108
	v_mov_b32_e32 v7, v108
	v_mov_b32_e32 v24, v108
	v_mov_b32_e32 v25, v108
	v_mov_b32_e32 v26, v108
	v_mov_b32_e32 v27, v108
	v_mov_b32_e32 v28, v108
	v_mov_b32_e32 v29, v108
	v_mov_b32_e32 v30, v108
	v_mov_b32_e32 v31, v108
	v_mov_b32_e32 v162, 0
	v_mov_b32_e32 v163, 0
	v_mov_b32_e32 v164, 0
	v_mov_b32_e32 v165, 0
	v_mov_b32_e32 v166, 0
	v_mov_b32_e32 v167, 0
	v_mov_b32_e32 v168, 0
	v_mov_b32_e32 v169, 0
	v_mov_b32_e32 v138, 0
	v_mov_b32_e32 v139, 0
	v_mov_b32_e32 v140, 0
	v_mov_b32_e32 v141, 0
	v_mov_b32_e32 v142, 0
	v_mov_b32_e32 v143, 0
	v_mov_b32_e32 v144, 0
	v_mov_b32_e32 v145, 0
	v_mov_b32_e32 v146, 0
	v_mov_b32_e32 v147, 0
	v_mov_b32_e32 v148, 0
	v_mov_b32_e32 v149, 0
	v_mov_b32_e32 v150, 0
	v_mov_b32_e32 v151, 0
	v_mov_b32_e32 v152, 0
	v_mov_b32_e32 v153, 0
	ds_read_b128 v[110:113], v107 offset:6656
	ds_read_b128 v[114:117], v107 offset:6688
	ds_read_b128 v[118:121], v107 offset:6720
	ds_read_b128 v[122:125], v107 offset:6752
	ds_read_b128 v[130:133], v107 offset:6784
	ds_read_b128 v[134:137], v107 offset:6816
	s_waitcnt lgkmcnt(0)

; DI int my_tid() { int t = threadIdx.x; asm volatile("" : "+v"(t)); return t; }
; DI float bf_lo(unsigned u) { return __uint_as_float(u << 16); }
; DI float bf_hi(unsigned u) { return __uint_as_float(u & 0xffff0000u); }
; DI void mla_item(PRef p, int j, int seq, int head, int qb, char* smem) {
;   const int tid = my_tid(), lane = tid & 63, w = tid >> 6, r = lane & 31, h = lane >> 5;
;   const int s0 = seq == 0 ? 0 : TP + (seq - 1) * SS;
;   const int S = seq == 0 ? TP : SS;
;   const int pos = qb * 256 + w * 32 + r;
;   const int tok = s0 + pos;
;   const short* Q = (const short*)(p.ws + OFF_Q);
;   const float* gq = p.in[10] + j * 96;
;   float qv[6][8];
;   float ss = 0.f;
; #pragma unroll
;   for (int ks = 0; ks < 6; ks++) {
;     u32x4 t = *(const u32x4*)(Q + (size_t)tok * 1152 + head * 96 + ks * 16 + 8 * h);
; #pragma unroll
;     for (int e = 0; e < 4; e++) {
;       qv[ks][2 * e] = bf_lo(t[e]);
;       qv[ks][2 * e + 1] = bf_hi(t[e]);
;     }
; #pragma unroll
;     for (int e = 0; e < 8; e++) ss += qv[ks][e] * qv[ks][e];
; DI void run_phase(PRef p, int ph, char* smem, int noatom) {
;     ...
;         for (int li = l; li < 384; li += nl) {
;           const int u = xj + 8 * (li >> 4);
;           mla_item(p, j, 1 + u / 12, u % 12, li & 15, smem);
.LBB0_170:
	s_ashr_i32 s8, s22, 1
	s_and_b32 s8, s8, -8
	s_or_b32 s14, s8, s52
	s_mul_hi_i32 s8, s14, 0x2aaaaaab
	s_lshr_b32 s9, s8, 31
	s_ashr_i32 s8, s8, 1
	s_add_i32 s15, s8, s9
	v_add_co_u32_e64 v0, s[8:9], s15, 1
	s_mul_i32 s15, s15, 12
	s_sub_i32 s16, s14, s15
	v_readfirstlane_b32 s14, v0
	s_lshl_b32 s14, s14, 12
	s_add_i32 s23, s14, 0x3000
	s_and_b64 s[14:15], s[8:9], exec
	v_mov_b32_e32 v6, v196
	s_cselect_b32 s14, 0, s23
	s_getpc_b64 s[28:29]
	s_add_u32 s28, s28, _ZL10ROPE_TURNS@rel32@lo+4
	s_addc_u32 s29, s29, _ZL10ROPE_TURNS@rel32@hi+12
	s_lshl_b32 s15, s22, 8
	v_lshrrev_b32_e32 v0, 2, v6
	v_ashrrev_i32_e32 v8, 1, v6
	v_and_b32_e32 v7, 8, v0
	v_and_b32_e32 v8, 0xffffffe0, v8
	s_and_b32 s15, s15, 0xf00
	v_lshlrev_b32_e32 v0, 3, v7
	v_add_u32_e32 v8, s15, v8
	global_load_dwordx4 v[30:33], v0, s[28:29]
	global_load_dwordx4 v[34:37], v0, s[28:29] offset:16
	global_load_dwordx4 v[38:41], v0, s[28:29] offset:32
	global_load_dwordx4 v[2:5], v0, s[28:29] offset:48
	v_and_or_b32 v6, v6, 31, v8
	v_mov_b64_e32 v[0:1], s[4:5]
	s_mul_i32 s28, s16, 0x60
	v_add_u32_e32 v102, s14, v6
	s_movk_i32 s15, 0x900
	s_ashr_i32 s29, s28, 31
	v_mad_i64_i32 v[0:1], s[34:35], v102, s15, v[0:1]
	s_waitcnt vmcnt(11)
	v_lshlrev_b32_e32 v128, 1, v7
	v_lshl_add_u64 v[0:1], s[28:29], 1, v[0:1]
	v_lshl_add_u64 v[0:1], v[0:1], 0, v[128:129]
	global_load_dwordx4 v[26:29], v[0:1], off offset:128
	global_load_dwordx4 v[22:25], v[0:1], off offset:160
	global_load_dwordx4 v[18:21], v[0:1], off offset:96
	v_and_b32_e32 v9, 64, v200
	v_xor_b32_e32 v8, 32, v200
	v_add_u32_e32 v9, 64, v9
	v_cmp_lt_i32_e32 vcc, v8, v9
	v_lshlrev_b32_e32 v128, 2, v7
	v_cvt_f64_i32_e32 v[42:43], v6
	v_cndmask_b32_e32 v8, v200, v8, vcc
	v_lshlrev_b32_e32 v103, 2, v8
	global_load_dwordx4 v[6:9], v[0:1], off
	global_load_dwordx4 v[10:13], v[0:1], off offset:32
	global_load_dwordx4 v[14:17], v[0:1], off offset:64
	s_and_b64 s[8:9], s[8:9], exec
	s_cselect_b32 s29, 0x80, 32
	s_mul_i32 s9, s16, 0x14000
	s_ashr_i32 s15, s14, 31
	s_mul_hi_i32 s8, s16, 0x14000
	s_add_u32 s9, s9, s14
	s_addc_u32 s8, s8, s15
	s_mulk_i32 s8, 0xc0
	s_mul_hi_u32 s30, s9, 0xc0
	s_add_i32 s30, s30, s8
	s_mulk_i32 s9, 0xc0
	s_add_u32 s8, s10, s9
	s_addc_u32 s9, s11, s30
	s_mul_i32 s35, s16, 0xa00000
	s_mul_hi_i32 s30, s16, 0xa00000
	s_add_u32 s35, s12, s35
	s_addc_u32 s30, s13, s30
	s_lshl_b64 s[14:15], s[14:15], 1
	s_add_u32 s14, s35, s14
	s_addc_u32 s15, s30, s15
	s_mov_b32 s39, 0x500000
	s_mov_b32 s30, 0x3e16c740
	s_mov_b32 s34, 1
	s_mov_b32 s23, 0
	s_mov_b32 s28, 2
	s_waitcnt vmcnt(9)
	v_mul_f64 v[0:1], v[30:31], v[42:43]
	v_mul_f64 v[44:45], v[32:33], v[42:43]
	v_floor_f64_e32 v[0:1], v[0:1]
	s_waitcnt vmcnt(6)
	v_mul_f64 v[54:55], v[2:3], v[42:43]
	v_floor_f64_e32 v[44:45], v[44:45]
	v_floor_f64_e32 v[54:55], v[54:55]
	v_fma_f64 v[0:1], v[30:31], v[42:43], -v[0:1]
	v_fma_f64 v[30:31], v[32:33], v[42:43], -v[44:45]
	v_fma_f64 v[2:3], v[2:3], v[42:43], -v[54:55]
	v_cvt_f32_f64_e32 v0, v[0:1]
	v_mul_f64 v[46:47], v[34:35], v[42:43]
	v_mul_f64 v[48:49], v[36:37], v[42:43]
	v_mul_f64 v[50:51], v[38:39], v[42:43]
	v_mul_f64 v[52:53], v[40:41], v[42:43]
	v_cvt_f32_f64_e32 v1, v[30:31]
	v_sin_f32_e32 v72, v0
	v_cos_f32_e32 v64, v0
	v_cvt_f32_f64_e32 v0, v[2:3]
	v_floor_f64_e32 v[46:47], v[46:47]
	v_floor_f64_e32 v[48:49], v[48:49]
	v_floor_f64_e32 v[50:51], v[50:51]
	v_floor_f64_e32 v[52:53], v[52:53]
	v_sin_f32_e32 v73, v1
	v_cos_f32_e32 v65, v1
	v_sin_f32_e32 v70, v0
	v_cos_f32_e32 v68, v0
	v_mul_f64 v[0:1], v[4:5], v[42:43]
	v_fma_f64 v[32:33], v[34:35], v[42:43], -v[46:47]
	v_fma_f64 v[34:35], v[36:37], v[42:43], -v[48:49]
	v_fma_f64 v[36:37], v[38:39], v[42:43], -v[50:51]
	v_fma_f64 v[38:39], v[40:41], v[42:43], -v[52:53]
	v_floor_f64_e32 v[44:45], v[0:1]
	global_load_dwordx4 v[0:3], v128, s[6:7] offset:256
	s_waitcnt vmcnt(4)
	v_lshlrev_b32_e32 v104, 16, v21
	v_and_b32_e32 v105, 0xffff0000, v21
	global_load_dwordx4 v[82:85], v128, s[6:7] offset:208
	global_load_dwordx4 v[86:89], v128, s[6:7] offset:192
	v_lshlrev_b32_e32 v108, 16, v20
	v_and_b32_e32 v109, 0xffff0000, v20
	v_lshlrev_b32_e32 v112, 16, v19
	v_and_b32_e32 v113, 0xffff0000, v19
	v_lshlrev_b32_e32 v116, 16, v18
	v_and_b32_e32 v117, 0xffff0000, v18
	global_load_dwordx4 v[18:21], v128, s[6:7] offset:144
	global_load_dwordx4 v[78:81], v128, s[6:7] offset:128
	global_load_dwordx4 v[60:63], v128, s[6:7] offset:80
	global_load_dwordx4 v[56:59], v128, s[6:7] offset:64
	global_load_dwordx4 v[50:53], v128, s[6:7]
	global_load_dwordx4 v[90:93], v128, s[6:7] offset:16
	s_waitcnt vmcnt(11)
	v_lshlrev_b32_e32 v156, 16, v6
	v_and_b32_e32 v157, 0xffff0000, v6
	v_lshlrev_b32_e32 v152, 16, v7
	v_and_b32_e32 v153, 0xffff0000, v7
	v_pk_mul_f32 v[6:7], v[156:157], v[156:157]
	v_pk_mul_f32 v[154:155], v[152:153], v[152:153]
	v_add_f32_e32 v6, v6, v7
	v_lshlrev_b32_e32 v150, 16, v8
	v_and_b32_e32 v151, 0xffff0000, v8
	v_add_f32_e32 v6, v154, v6
	v_lshlrev_b32_e32 v146, 16, v9
	v_and_b32_e32 v147, 0xffff0000, v9
	v_pk_mul_f32 v[8:9], v[150:151], v[150:151]
	v_add_f32_e32 v6, v155, v6
	v_add_f32_e32 v6, v8, v6
	v_pk_mul_f32 v[148:149], v[146:147], v[146:147]
	v_add_f32_e32 v6, v9, v6
	s_waitcnt vmcnt(10)
	v_lshlrev_b32_e32 v144, 16, v10
	v_and_b32_e32 v145, 0xffff0000, v10
	v_add_f32_e32 v6, v148, v6
	v_lshlrev_b32_e32 v140, 16, v11
	v_and_b32_e32 v141, 0xffff0000, v11
	v_pk_mul_f32 v[10:11], v[144:145], v[144:145]
	v_add_f32_e32 v6, v149, v6
	v_add_f32_e32 v6, v10, v6
	v_pk_mul_f32 v[142:143], v[140:141], v[140:141]
	v_add_f32_e32 v6, v11, v6
	v_lshlrev_b32_e32 v138, 16, v12
	v_and_b32_e32 v139, 0xffff0000, v12
	v_add_f32_e32 v6, v142, v6
	v_lshlrev_b32_e32 v134, 16, v13
	v_and_b32_e32 v135, 0xffff0000, v13
	v_pk_mul_f32 v[12:13], v[138:139], v[138:139]
	v_add_f32_e32 v6, v143, v6
	v_add_f32_e32 v6, v12, v6
	v_pk_mul_f32 v[136:137], v[134:135], v[134:135]
	v_add_f32_e32 v6, v13, v6
	s_waitcnt vmcnt(9)
; DI float rsqrt_f(float x) { return __builtin_amdgcn_rsqf(x); }
; DI void mla_item(PRef p, int j, int seq, int head, int qb, char* smem) {
;     ...
; #pragma unroll
;     for (int e = 0; e < 8; e++) ss += qv[ks][e] * qv[ks][e];
;   }
;   ss += __shfl_xor(ss, 32);
;   const float f = rsqrt_f(ss * (1.f / 96.f) + EPS);
;   const float sc = 0.10206207261596575f * LOG2E;
; #pragma unroll
;   for (int ks = 0; ks < 6; ks++)
; #pragma unroll
;     for (int e = 0; e < 8; e++) qv[ks][e] *= f * gq[ks * 16 + 8 * h + e];
	v_lshlrev_b32_e32 v132, 16, v14
	v_and_b32_e32 v133, 0xffff0000, v14
	v_add_f32_e32 v6, v136, v6
	v_lshlrev_b32_e32 v126, 16, v15
	v_and_b32_e32 v127, 0xffff0000, v15
	v_pk_mul_f32 v[14:15], v[132:133], v[132:133]
	v_add_f32_e32 v6, v137, v6
	v_add_f32_e32 v6, v14, v6
	v_pk_mul_f32 v[130:131], v[126:127], v[126:127]
	v_add_f32_e32 v6, v15, v6
	v_lshlrev_b32_e32 v124, 16, v16
	v_and_b32_e32 v125, 0xffff0000, v16
	v_add_f32_e32 v6, v130, v6
	v_lshlrev_b32_e32 v120, 16, v17
	v_and_b32_e32 v121, 0xffff0000, v17
	v_pk_mul_f32 v[16:17], v[124:125], v[124:125]
	v_add_f32_e32 v6, v131, v6
	v_add_f32_e32 v6, v16, v6
	v_pk_mul_f32 v[122:123], v[120:121], v[120:121]
	v_add_f32_e32 v6, v17, v6
	v_add_f32_e32 v6, v122, v6
	v_pk_mul_f32 v[118:119], v[116:117], v[116:117]
	v_add_f32_e32 v6, v123, v6
	v_add_f32_e32 v6, v118, v6
	v_pk_mul_f32 v[114:115], v[112:113], v[112:113]
	v_add_f32_e32 v6, v119, v6
	v_add_f32_e32 v6, v114, v6
	v_pk_mul_f32 v[110:111], v[108:109], v[108:109]
	v_add_f32_e32 v6, v115, v6
	v_add_f32_e32 v6, v110, v6
	v_pk_mul_f32 v[106:107], v[104:105], v[104:105]
	v_add_f32_e32 v6, v111, v6
	v_lshlrev_b32_e32 v40, 16, v26
	v_and_b32_e32 v41, 0xffff0000, v26
	v_add_f32_e32 v6, v106, v6
	v_pk_mul_f32 v[100:101], v[40:41], v[40:41]
	v_add_f32_e32 v6, v107, v6
	v_cvt_f32_f64_e32 v30, v[32:33]
	v_cvt_f32_f64_e32 v33, v[38:39]
	v_lshlrev_b32_e32 v38, 16, v27
	v_and_b32_e32 v39, 0xffff0000, v27
	v_add_f32_e32 v6, v100, v6
	v_pk_mul_f32 v[96:97], v[38:39], v[38:39]
	v_add_f32_e32 v6, v101, v6
	v_cvt_f32_f64_e32 v32, v[36:37]
	v_lshlrev_b32_e32 v36, 16, v28
	v_and_b32_e32 v37, 0xffff0000, v28
	v_add_f32_e32 v6, v96, v6
	v_pk_mul_f32 v[54:55], v[36:37], v[36:37]
	v_add_f32_e32 v6, v97, v6
	v_cvt_f32_f64_e32 v31, v[34:35]
	v_lshlrev_b32_e32 v34, 16, v29
	v_and_b32_e32 v35, 0xffff0000, v29
	v_add_f32_e32 v6, v54, v6
	v_pk_mul_f32 v[46:47], v[34:35], v[34:35]
	v_add_f32_e32 v6, v55, v6
	v_lshlrev_b32_e32 v26, 16, v22
	v_and_b32_e32 v27, 0xffff0000, v22
	v_add_f32_e32 v6, v46, v6
	v_sin_f32_e32 v76, v30
	v_cos_f32_e32 v74, v30
	v_sin_f32_e32 v77, v31
	v_cos_f32_e32 v75, v31
	v_sin_f32_e32 v66, v32
	v_cos_f32_e32 v30, v32
	v_sin_f32_e32 v67, v33
	v_cos_f32_e32 v31, v33
	v_lshlrev_b32_e32 v32, 16, v25
	v_and_b32_e32 v33, 0xffff0000, v25
	v_lshlrev_b32_e32 v28, 16, v24
	v_and_b32_e32 v29, 0xffff0000, v24
	v_lshlrev_b32_e32 v24, 16, v23
	v_and_b32_e32 v25, 0xffff0000, v23
	v_pk_mul_f32 v[22:23], v[26:27], v[26:27]
	v_add_f32_e32 v6, v47, v6
	v_add_f32_e32 v6, v22, v6
	v_pk_mul_f32 v[98:99], v[24:25], v[24:25]
	v_add_f32_e32 v6, v23, v6
	v_add_f32_e32 v6, v98, v6
	v_pk_mul_f32 v[94:95], v[28:29], v[28:29]
	v_add_f32_e32 v6, v99, v6
	v_add_f32_e32 v6, v94, v6
	v_pk_mul_f32 v[48:49], v[32:33], v[32:33]
	v_add_f32_e32 v6, v95, v6
	v_add_f32_e32 v6, v48, v6
	v_add_f32_e32 v6, v49, v6
	ds_bpermute_b32 v7, v103, v6
	v_fma_f64 v[4:5], v[4:5], v[42:43], -v[44:45]
	v_cvt_f32_f64_e32 v4, v[4:5]
	v_sin_f32_e32 v71, v4
	v_cos_f32_e32 v69, v4
	s_waitcnt lgkmcnt(0)
	v_add_f32_e32 v4, v6, v7
	v_fmamk_f32 v4, v4, 0x3c2aaaab, v198
	v_rsq_f32_e32 v48, v4
	global_load_dwordx4 v[12:15], v128, s[6:7] offset:272
	global_load_dwordx4 v[4:7], v128, s[6:7] offset:336
	global_load_dwordx4 v[8:11], v128, s[6:7] offset:320
	s_waitcnt vmcnt(4)
	v_pk_mul_f32 v[16:17], v[50:51], v[48:49] op_sel_hi:[1,0]
	s_nop 0
	v_pk_mul_f32 v[46:47], v[16:17], v[156:157]
	v_pk_mul_f32 v[16:17], v[52:53], v[48:49] op_sel_hi:[1,0]
	v_pk_mul_f32 v[0:1], v[0:1], v[48:49] op_sel_hi:[1,0]
	v_pk_mul_f32 v[50:51], v[16:17], v[152:153]
	s_waitcnt vmcnt(3)
	v_pk_mul_f32 v[16:17], v[90:91], v[48:49] op_sel_hi:[1,0]
	s_nop 0
	v_pk_mul_f32 v[52:53], v[16:17], v[150:151]
	v_pk_mul_f32 v[16:17], v[92:93], v[48:49] op_sel_hi:[1,0]
	v_mov_b32_e32 v150, v196
	v_pk_mul_f32 v[54:55], v[16:17], v[146:147]
	v_pk_mul_f32 v[16:17], v[56:57], v[48:49] op_sel_hi:[1,0]
	s_nop 0
	v_pk_mul_f32 v[56:57], v[16:17], v[144:145]
	v_pk_mul_f32 v[16:17], v[58:59], v[48:49] op_sel_hi:[1,0]
	v_ashrrev_i32_e32 v151, 4, v150
	v_pk_mul_f32 v[58:59], v[16:17], v[140:141]
	v_pk_mul_f32 v[16:17], v[60:61], v[48:49] op_sel_hi:[1,0]
	v_lshlrev_b32_e32 v92, 3, v150
	v_pk_mul_f32 v[60:61], v[16:17], v[138:139]
	v_pk_mul_f32 v[16:17], v[62:63], v[48:49] op_sel_hi:[1,0]
	v_add_u32_e32 v96, 0x2000, v92
	v_pk_mul_f32 v[62:63], v[16:17], v[134:135]
	v_pk_mul_f32 v[16:17], v[78:79], v[48:49] op_sel_hi:[1,0]
	v_ashrrev_i32_e32 v93, 31, v92
	v_pk_mul_f32 v[78:79], v[16:17], v[132:133]
	v_pk_mul_f32 v[16:17], v[80:81], v[48:49] op_sel_hi:[1,0]
	v_ashrrev_i32_e32 v97, 31, v96
	v_pk_mul_f32 v[80:81], v[16:17], v[126:127]
	v_pk_mul_f32 v[16:17], v[18:19], v[48:49] op_sel_hi:[1,0]
	v_pk_mul_f32 v[18:19], v[82:83], v[48:49] op_sel_hi:[1,0]
	v_mov_b64_e32 v[82:83], s[14:15]
	s_mov_b32 s14, 0x28000
	v_pk_mul_f32 v[22:23], v[16:17], v[124:125]
	v_pk_mul_f32 v[16:17], v[20:21], v[48:49] op_sel_hi:[1,0]
	v_mad_i64_i32 v[90:91], s[14:15], v151, s14, v[82:83]
	v_pk_mul_f32 v[42:43], v[16:17], v[120:121]
	v_pk_mul_f32 v[16:17], v[86:87], v[48:49] op_sel_hi:[1,0]
	s_add_u32 s14, s8, 0x6000
	v_pk_mul_f32 v[44:45], v[16:17], v[116:117]
	v_pk_mul_f32 v[16:17], v[88:89], v[48:49] op_sel_hi:[1,0]
	v_pk_mul_f32 v[20:21], v[84:85], v[48:49] op_sel_hi:[1,0]
	v_lshlrev_b32_e32 v49, 4, v150
	v_lshlrev_b64 v[100:101], 1, v[92:93]
	v_add_u32_e32 v94, 0x1000, v92
	v_lshlrev_b64 v[106:107], 1, v[96:97]
	s_addc_u32 s15, s9, 0
	v_and_b32_e32 v128, 0xf0, v49
	v_lshl_add_u64 v[82:83], s[8:9], 0, v[100:101]
	v_ashrrev_i32_e32 v95, 31, v94
	v_lshl_add_u64 v[98:99], s[8:9], 0, v[106:107]
	v_lshl_add_u64 v[100:101], s[14:15], 0, v[100:101]
	v_pk_mul_f32 v[18:19], v[18:19], v[108:109]
	v_pk_mul_f32 v[20:21], v[20:21], v[104:105]
	v_lshlrev_b64 v[104:105], 1, v[94:95]
	global_load_dwordx4 v[108:111], v[98:99], off
	global_load_dwordx4 v[120:123], v[100:101], off
	v_lshl_add_u64 v[98:99], v[90:91], 0, v[128:129]
	v_add_co_u32_e32 v90, vcc, s39, v98
	v_lshl_add_u64 v[100:101], s[14:15], 0, v[104:105]
	v_lshl_add_u64 v[86:87], s[8:9], 0, v[104:105]
	v_addc_co_u32_e32 v91, vcc, 0, v99, vcc
	global_load_dwordx4 v[124:127], v[100:101], off
	v_lshl_add_u64 v[100:101], s[14:15], 0, v[106:107]
	v_pk_mul_f32 v[16:17], v[16:17], v[112:113]
	global_load_dwordx4 v[82:85], v[82:83], off
	s_movk_i32 s14, 0xd0
	global_load_dwordx4 v[86:89], v[86:87], off
	s_nop 0
	global_load_dwordx4 v[112:115], v[98:99], off
	global_load_dwordx4 v[116:119], v[90:91], off
	global_load_dwordx4 v[130:133], v[100:101], off
	global_load_dwordx4 v[134:137], v[98:99], off offset:256
	global_load_dwordx4 v[138:141], v[90:91], off offset:256
	v_pk_mul_f32 v[90:91], v[0:1], v[40:41]
	v_pk_mul_f32 v[0:1], v[2:3], v[48:49] op_sel_hi:[1,0]
	v_mul_hi_i32 v3, v150, s41
	v_pk_mul_f32 v[142:143], v[0:1], v[38:39]
	s_waitcnt vmcnt(12)
; DI void mla_item(PRef p, int j, int seq, int head, int qb, char* smem) {
;     ...
;   for (int e = 0; e < 8; e++) {
;     float cs, sn;
;     rope_cs(pos, 8 * h + e, cs, sn);
;     float x1 = qv[4][e], x2 = qv[5][e];
;     qv[4][e] = x1 * cs - x2 * sn;
;     qv[5][e] = x1 * sn + x2 * cs;
;   }
;   bf16x8 qf[6];
; #pragma unroll
;   for (int ks = 0; ks < 6; ks++) {
;     u32x4 t;
; #pragma unroll
;     for (int e = 0; e < 4; e++) t[e] = pack_bf16(qv[ks][2 * e] * sc, qv[ks][2 * e + 1] * sc);
;     qf[ks] = __builtin_bit_cast(bf16x8, t);
;   }
	v_pk_mul_f32 v[0:1], v[12:13], v[48:49] op_sel_hi:[1,0]
	s_nop 0
	v_pk_mul_f32 v[12:13], v[0:1], v[36:37]
	v_pk_mul_f32 v[0:1], v[14:15], v[48:49] op_sel_hi:[1,0]
	s_nop 0
	v_pk_mul_f32 v[14:15], v[0:1], v[34:35]
	s_waitcnt vmcnt(10)
	v_pk_mul_f32 v[0:1], v[8:9], v[48:49] op_sel_hi:[1,0]
	s_nop 0
	v_pk_mul_f32 v[8:9], v[0:1], v[26:27]
	v_pk_mul_f32 v[0:1], v[10:11], v[48:49] op_sel_hi:[1,0]
	s_nop 0
	v_pk_mul_f32 v[10:11], v[0:1], v[24:25]
	v_pk_mul_f32 v[0:1], v[4:5], v[48:49] op_sel_hi:[1,0]
	v_pk_mul_f32 v[4:5], v[80:81], s[30:31] op_sel_hi:[1,0]
	v_pk_mul_f32 v[24:25], v[0:1], v[28:29]
	v_pk_mul_f32 v[0:1], v[6:7], v[48:49] op_sel_hi:[1,0]
	v_lshrrev_b32_e32 v6, 31, v3
	v_pk_mul_f32 v[26:27], v[0:1], v[32:33]
	v_pk_mul_f32 v[0:1], v[8:9], v[64:65]
	v_lshrrev_b32_e32 v3, 1, v3
	v_pk_fma_f32 v[28:29], v[90:91], v[72:73], v[0:1]
	v_pk_mul_f32 v[0:1], v[10:11], v[74:75]
	v_add_u32_e32 v3, v3, v6
	v_pk_fma_f32 v[144:145], v[142:143], v[76:77], v[0:1]
	v_pk_mul_f32 v[0:1], v[24:25], v[30:31]
	v_add_lshl_u32 v104, v3, v150, 4
	v_pk_fma_f32 v[146:147], v[12:13], v[66:67], v[0:1]
	v_pk_mul_f32 v[0:1], v[26:27], v[68:69]
	v_add_u32_e32 v3, 0x200, v150
	v_pk_fma_f32 v[148:149], v[14:15], v[70:71], v[0:1]
	v_pk_mul_f32 v[0:1], v[46:47], s[30:31] op_sel_hi:[1,0]
	v_mul_hi_i32 v6, v3, s41
	v_cvt_pk_bf16_f32 v48, v0, v1
	v_pk_mul_f32 v[0:1], v[50:51], s[30:31] op_sel_hi:[1,0]
	v_lshrrev_b32_e32 v7, 31, v6
	v_cvt_pk_bf16_f32 v49, v0, v1
	v_pk_mul_f32 v[0:1], v[52:53], s[30:31] op_sel_hi:[1,0]
	v_lshrrev_b32_e32 v6, 1, v6
	v_cvt_pk_bf16_f32 v50, v0, v1
	v_pk_mul_f32 v[0:1], v[54:55], s[30:31] op_sel_hi:[1,0]
	v_add_u32_e32 v6, v6, v7
	v_cvt_pk_bf16_f32 v51, v0, v1
	v_pk_mul_f32 v[0:1], v[56:57], s[30:31] op_sel_hi:[1,0]
	v_add_lshl_u32 v105, v6, v3, 4
	v_cvt_pk_bf16_f32 v52, v0, v1
	v_pk_mul_f32 v[0:1], v[58:59], s[30:31] op_sel_hi:[1,0]
	v_add_u32_e32 v3, 0x400, v150
	v_cvt_pk_bf16_f32 v53, v0, v1
	v_pk_mul_f32 v[0:1], v[60:61], s[30:31] op_sel_hi:[1,0]
	v_mul_hi_i32 v6, v3, s41
	v_cvt_pk_bf16_f32 v54, v0, v1
	v_pk_mul_f32 v[0:1], v[62:63], s[30:31] op_sel_hi:[1,0]
	v_lshrrev_b32_e32 v7, 31, v6
	v_cvt_pk_bf16_f32 v55, v0, v1
	v_pk_mul_f32 v[0:1], v[78:79], s[30:31] op_sel_hi:[1,0]
	v_lshrrev_b32_e32 v6, 1, v6
	v_cvt_pk_bf16_f32 v56, v0, v1
	v_lshlrev_b32_e32 v0, 1, v150
	v_lshrrev_b32_e32 v1, 1, v150
	v_add_u32_e32 v6, v6, v7
	v_and_b32_e32 v0, 8, v0
	v_and_b32_e32 v2, 4, v1
	v_add_lshl_u32 v106, v6, v3, 4
	v_and_b32_e32 v3, 19, v150
	v_and_b32_e32 v78, 16, v1
	v_or3_b32 v0, v3, v0, v2
	v_mad_u32_u24 v107, v0, s14, v78
	v_mad_u64_u32 v[100:101], s[14:15], v151, s36, v[128:129]
	v_add_u32_e32 v0, 0x6800, v100
	s_waitcnt vmcnt(6)
	ds_write_b128 v104, v[82:85]
	s_waitcnt vmcnt(5)
	ds_write_b128 v105, v[86:89]
	ds_write_b128 v106, v[108:111]
	s_waitcnt vmcnt(4)
	ds_write_b128 v100, v[112:115] offset:26624
	s_waitcnt vmcnt(3)
	ds_write_b128 v100, v[116:119] offset:35328
	ds_write_b128 v104, v[120:123] offset:44032
	ds_write_b128 v105, v[124:127] offset:44032
	s_waitcnt vmcnt(2)
	ds_write_b128 v106, v[130:133] offset:44032
	s_waitcnt vmcnt(1)
	ds_write_b128 v0, v[134:137] offset:44032
	s_waitcnt vmcnt(0)
	ds_write_b128 v0, v[138:141] offset:52736
	s_waitcnt lgkmcnt(0)
	s_barrier
; #define KLOAD(kf_, base)                                                                       \
;   { _Pragma("unroll") for (int ks = 0; ks < NKS; ks++) kf_[ks] = *(const bf16x8*)((base) + kfo + ks * 32); }
; #define QKM(dst, kf_)                                                                          \
;   {                                                                                            \
;     _Pragma("unroll") for (int i = 0; i < 16; i++) dst[i] = 0.f;                               \
;     _Pragma("unroll") for (int ks = 0; ks < NKS; ks++) dst = MFMA(kf_[ks], qf[ks], dst);       \
;   }
; template <int DK>
; DI void attn_core(const bf16x8 (&qf)[DK / 16], const short* Kg, const short* VTg, size_t ldvt, int ntiles, char* smem,
;                   f32x16 (&O)[2], float& lsum) {
;     ...
;   f32x16 Sc;
;   {
;     bf16x8 kf[NKS];
;     KLOAD(kf, smem);
;     QKM(Sc, kf);
;   }
; DI void mla_item(PRef p, int j, int seq, int head, int qb, char* smem) {
;     ...
;   bf16x8 qf[6];
; #pragma unroll
;   for (int ks = 0; ks < 6; ks++) {
;     u32x4 t;
; #pragma unroll
;     for (int e = 0; e < 4; e++) t[e] = pack_bf16(qv[ks][2 * e] * sc, qv[ks][2 * e + 1] * sc);
;     qf[ks] = __builtin_bit_cast(bf16x8, t);
;   }
	ds_read_b128 v[0:3], v107
	v_cvt_pk_bf16_f32 v57, v4, v5
	v_pk_mul_f32 v[4:5], v[22:23], s[30:31] op_sel_hi:[1,0]
	v_mov_b32_e32 v108, 0
	v_cvt_pk_bf16_f32 v58, v4, v5
	v_pk_mul_f32 v[4:5], v[42:43], s[30:31] op_sel_hi:[1,0]
	s_add_i32 s14, s29, -1
	v_cvt_pk_bf16_f32 v59, v4, v5
	v_pk_mul_f32 v[4:5], v[44:45], s[30:31] op_sel_hi:[1,0]
	s_mov_b32 s15, 0
	v_cvt_pk_bf16_f32 v60, v4, v5
	ds_read_b128 v[4:7], v107 offset:32
	s_waitcnt lgkmcnt(1)
	v_mfma_f32_32x32x16_bf16 v[32:47], v[0:3], v[48:51], 0
	v_mul_f32_e64 v0, v16, s30
	v_mul_f32_e64 v1, v17, s30
	v_mov_b32_e32 v16, 0
	v_cvt_pk_bf16_f32 v61, v0, v1
	v_mul_f32_e64 v0, v18, s30
	v_mul_f32_e64 v1, v19, s30
	v_mov_b32_e32 v17, v108
	v_cvt_pk_bf16_f32 v62, v0, v1
	v_pk_mul_f32 v[0:1], v[20:21], s[30:31] op_sel_hi:[1,0]
	s_waitcnt lgkmcnt(0)
	v_mfma_f32_32x32x16_bf16 v[32:47], v[4:7], v[52:55], v[32:47]
	v_cvt_pk_bf16_f32 v63, v0, v1
	ds_read_b128 v[0:3], v107 offset:64
	v_mul_f32_e64 v4, v8, v72
	v_mul_f32_e64 v5, v9, v73
	v_mov_b32_e32 v18, v108
	v_pk_fma_f32 v[4:5], v[90:91], v[64:65], v[4:5] neg_lo:[0,0,1] neg_hi:[0,0,1]
	v_mov_b32_e32 v19, v108
	v_pk_mul_f32 v[4:5], v[4:5], s[30:31] op_sel_hi:[1,0]
	v_mov_b32_e32 v20, v108
	v_cvt_pk_bf16_f32 v64, v4, v5
	v_pk_mul_f32 v[4:5], v[10:11], v[76:77]
	v_mov_b32_e32 v10, v108
	v_pk_fma_f32 v[8:9], v[142:143], v[74:75], v[4:5] neg_lo:[0,0,1] neg_hi:[0,0,1]
	ds_read_b128 v[4:7], v107 offset:96
	s_waitcnt lgkmcnt(1)
	v_mfma_f32_32x32x16_bf16 v[32:47], v[0:3], v[56:59], v[32:47]
	v_mul_f32_e64 v0, v8, s30
	v_mul_f32_e64 v1, v9, s30
	v_mov_b32_e32 v8, v108
	v_cvt_pk_bf16_f32 v65, v0, v1
	v_mul_f32_e64 v0, v24, v66
	v_mul_f32_e64 v1, v25, v67
	v_mov_b32_e32 v9, v108
	v_pk_fma_f32 v[0:1], v[12:13], v[30:31], v[0:1] neg_lo:[0,0,1] neg_hi:[0,0,1]
	v_mov_b32_e32 v11, v108
	v_pk_mul_f32 v[0:1], v[0:1], s[30:31] op_sel_hi:[1,0]
	s_waitcnt lgkmcnt(0)
	v_mfma_f32_32x32x16_bf16 v[32:47], v[4:7], v[60:63], v[32:47]
	v_cvt_pk_bf16_f32 v66, v0, v1
	ds_read_b128 v[0:3], v107 offset:128
	v_mul_f32_e64 v4, v26, v70
	v_mul_f32_e64 v5, v27, v71
	v_mov_b32_e32 v12, v108
	v_pk_fma_f32 v[4:5], v[14:15], v[68:69], v[4:5] neg_lo:[0,0,1] neg_hi:[0,0,1]
	v_mov_b32_e32 v13, v108
	v_pk_mul_f32 v[4:5], v[4:5], s[30:31] op_sel_hi:[1,0]
	v_mov_b32_e32 v14, v108
	v_cvt_pk_bf16_f32 v67, v4, v5
	v_pk_mul_f32 v[4:5], v[28:29], s[30:31] op_sel_hi:[1,0]
	v_mov_b32_e32 v15, v108
	v_cvt_pk_bf16_f32 v68, v4, v5
	ds_read_b128 v[4:7], v107 offset:160
	s_waitcnt lgkmcnt(1)
	v_mfma_f32_32x32x16_bf16 v[32:47], v[0:3], v[64:67], v[32:47]
	v_mul_f32_e64 v0, v144, s30
	v_mul_f32_e64 v1, v145, s30
	v_mov_b32_e32 v2, v108
	v_cvt_pk_bf16_f32 v69, v0, v1
	v_mul_f32_e64 v0, v146, s30
	v_mul_f32_e64 v1, v147, s30
	v_mov_b32_e32 v3, v108
	v_cvt_pk_bf16_f32 v70, v0, v1
	v_pk_mul_f32 v[0:1], v[148:149], s[30:31] op_sel_hi:[1,0]
	v_mov_b32_e32 v21, v108
	v_cvt_pk_bf16_f32 v71, v0, v1
	v_and_b32_e32 v0, 31, v150
	v_mad_u32_u24 v101, v0, s36, v78
	s_waitcnt lgkmcnt(0)
	v_mfma_f32_32x32x16_bf16 v[32:47], v[4:7], v[68:71], v[32:47]
	v_mov_b32_e32 v0, 0
	v_mov_b32_e32 v1, v108
	v_mov_b32_e32 v4, v108
	v_mov_b32_e32 v5, v108
	v_mov_b32_e32 v6, v108
	v_mov_b32_e32 v7, v108
	v_mov_b32_e32 v22, v108
	v_mov_b32_e32 v23, v108
	v_mov_b32_e32 v24, v108
	v_mov_b32_e32 v25, v108
	v_mov_b32_e32 v26, v108
	v_mov_b32_e32 v27, v108
	v_mov_b32_e32 v28, v108
	v_mov_b32_e32 v29, v108
	v_mov_b32_e32 v30, v108
	v_mov_b32_e32 v31, v108
	v_mov_b32_e32 v162, 0
	v_mov_b32_e32 v163, 0
	v_mov_b32_e32 v164, 0
	v_mov_b32_e32 v165, 0
	v_mov_b32_e32 v166, 0
	v_mov_b32_e32 v167, 0
	v_mov_b32_e32 v168, 0
	v_mov_b32_e32 v169, 0
	v_mov_b32_e32 v138, 0
	v_mov_b32_e32 v139, 0
	v_mov_b32_e32 v140, 0
	v_mov_b32_e32 v141, 0
	v_mov_b32_e32 v142, 0
	v_mov_b32_e32 v143, 0
	v_mov_b32_e32 v144, 0
	v_mov_b32_e32 v145, 0
	v_mov_b32_e32 v146, 0
	v_mov_b32_e32 v147, 0
	v_mov_b32_e32 v148, 0
	v_mov_b32_e32 v149, 0
	v_mov_b32_e32 v150, 0
	v_mov_b32_e32 v151, 0
	v_mov_b32_e32 v152, 0
	v_mov_b32_e32 v153, 0
	ds_read_b128 v[110:113], v107 offset:6656
	ds_read_b128 v[114:117], v107 offset:6688
	ds_read_b128 v[118:121], v107 offset:6720
	ds_read_b128 v[122:125], v107 offset:6752
	ds_read_b128 v[130:133], v107 offset:6784
	ds_read_b128 v[134:137], v107 offset:6816
	s_waitcnt lgkmcnt(0)

; DI int my_tid() { int t = threadIdx.x; asm volatile("" : "+v"(t)); return t; }
; #define KLOAD(kf_, base)                                                                       \
;   { _Pragma("unroll") for (int ks = 0; ks < NKS; ks++) kf_[ks] = *(const bf16x8*)((base) + kfo + ks * 32); }
; #define VLOAD(vf_, base)                                                                       \
;   { _Pragma("unroll") for (int q = 0; q < 4; q++) vf_[q] = *(const bf16x8*)((base) + vfo + (q >> 1) * 32 * VROW + (q & 1) * 32); }
; #define SB() __builtin_amdgcn_sched_barrier(0)
; template <int DK>
; DI void attn_core(const bf16x8 (&qf)[DK / 16], const short* Kg, const short* VTg, size_t ldvt, int ntiles, char* smem,
;                   f32x16 (&O)[2], float& lsum) {
;     ...
;   AGLOAD(0);
;   ASTORE(0);
;   AGLOAD(ntiles > 1 ? 1 : 0);
;   ASTORE(1);
;   __syncthreads();
;   f32x16 Sc;
;   {
;     bf16x8 kf[NKS];
;     KLOAD(kf, smem);
;     QKM(Sc, kf);
;   }
;   int sc = 0, sn = 1, sw = 2;
;   for (int t = 0; t < ntiles; t++) {
;     const int tn = t + 2 < ntiles ? t + 2 : ntiles - 1;
;     AGLOAD(tn);
;     const char* cur = smem + sc * ST;
;     const char* nxt = smem + sn * ST;
;     f32x16 Sn;
;     bf16x8 pa, pb, qa, qb;
;     bf16x8 kf[NKS], vf[4];
;     KLOAD(kf, cur + 32 * KROW);
;     SB();
;     SOFTMAX(Sc, pa, pb, l0);
;     SB();
;     QKM(Sn, kf);
;     SB();
;     KLOAD(kf, cur + 64 * KROW);
;     VLOAD(vf, cur);
;     SB();
;     SOFTMAX(Sn, qa, qb, l0);
; DI void memattn_item(PRef p, int layer, int mt, int head, char* smem) {
;   const int tid = my_tid(), lane = tid & 63, w = tid >> 6, r = lane & 31, h = lane >> 5;
;   const int tok = mt * 256 + w * 32 + r;
;   const int seq = tok_seq(mt * 256);
;   const short* Q = (const short*)(p.ws + OFF_QMEM);
;   bf16x8 qf[4];
; #pragma unroll
;   for (int ks = 0; ks < 4; ks++) qf[ks] = *(const bf16x8*)(Q + (size_t)tok * 256 + head * 64 + ks * 16 + 8 * h);
;   const size_t hb = ((size_t)(layer * NSEQ + seq) * 4 + head) * 256 * 64;
;   f32x16 O[2];
;   float lsum;
;   attn_core<64>(qf, (const short*)(p.ws + OFF_KMEM) + hb, (const short*)(p.ws + OFF_VMEM) + hb, 256, 2, smem, O, lsum);
.LBB0_175:
	v_mov_b32_e32 v2, v196
	s_ashr_i32 s14, s16, 2
	s_lshl_b32 s15, s14, 8
	v_ashrrev_i32_e32 v0, 1, v2
	v_and_b32_e32 v0, 0xffffffe0, v0
	v_add_u32_e32 v0, s15, v0
	v_and_or_b32 v80, v2, 31, v0
	v_ashrrev_i32_e32 v81, 31, v80
	s_and_b32 s20, s16, 3
	v_lshlrev_b64 v[0:1], 9, v[80:81]
	v_lshl_add_u64 v[0:1], s[4:5], 0, v[0:1]
	s_lshl_b32 s30, s20, 7
	v_lshrrev_b32_e32 v2, 1, v2
	v_lshl_add_u64 v[0:1], v[0:1], 0, s[30:31]
	s_waitcnt vmcnt(7)
	v_and_b32_e32 v128, 16, v2
	v_lshl_add_u64 v[0:1], v[0:1], 0, v[128:129]
	s_addk_i32 s15, 0xc000
	v_mov_b32_e32 v2, v196
	global_load_dwordx4 v[60:63], v[0:1], off
	global_load_dwordx4 v[56:59], v[0:1], off offset:32
	global_load_dwordx4 v[52:55], v[0:1], off offset:64
	global_load_dwordx4 v[48:51], v[0:1], off offset:96
	s_lshr_b32 s15, s15, 12
	s_add_i32 s15, s15, 1
	v_lshlrev_b32_e32 v0, 1, v2
	v_and_b32_e32 v10, 8, v0
	v_ashrrev_i32_e32 v0, 31, v2
	s_cmp_gt_i32 s14, 63
	v_lshrrev_b32_e32 v0, 29, v0
	s_cselect_b32 s14, s15, 0
	s_mul_i32 s15, s28, 17
	v_add_u32_e32 v0, v2, v0
	s_add_i32 s14, s14, s15
	s_mov_b32 s15, s31
	v_lshrrev_b32_e32 v0, 3, v0
	s_lshl_b64 s[18:19], s[14:15], 17
	s_lshl_b32 s14, s20, 15
	v_add_lshl_u32 v81, v0, v2, 4
	v_add_u32_e32 v0, 0x200, v2
	s_or_b32 s18, s18, s14
	v_ashrrev_i32_e32 v1, 31, v0
	v_lshlrev_b32_e32 v4, 4, v2
	s_add_u32 s14, s10, s18
	v_lshrrev_b32_e32 v1, 29, v1
	v_and_b32_e32 v128, 0xf0, v4
	v_lshlrev_b32_e32 v4, 3, v2
	s_addc_u32 s15, s11, s19
	v_add_u32_e32 v1, v0, v1
	v_ashrrev_i32_e32 v16, 4, v2
	v_ashrrev_i32_e32 v5, 31, v4
	s_add_u32 s18, s12, s18
	v_lshrrev_b32_e32 v1, 3, v1
	v_ashrrev_i32_e32 v17, 31, v16
	v_lshlrev_b64 v[18:19], 1, v[4:5]
	v_add_u32_e32 v4, 0x1000, v4
	s_addc_u32 s19, s13, s19
	v_add_lshl_u32 v92, v1, v0, 4
	v_lshlrev_b64 v[0:1], 9, v[16:17]
	v_ashrrev_i32_e32 v5, 31, v4
	v_lshrrev_b32_e32 v3, 1, v2
	v_lshl_add_u64 v[8:9], s[18:19], 0, v[0:1]
	v_lshl_add_u64 v[0:1], s[14:15], 0, v[18:19]
	v_lshlrev_b64 v[20:21], 1, v[4:5]
	v_and_b32_e32 v32, 31, v2
	v_and_b32_e32 v11, 4, v3
	v_and_b32_e32 v12, 19, v2
	v_and_b32_e32 v33, 16, v3
	global_load_dwordx4 v[0:3], v[0:1], off
	v_lshl_add_u64 v[4:5], s[14:15], 0, v[20:21]
	v_lshl_add_u64 v[84:85], v[8:9], 0, v[128:129]
	global_load_dwordx4 v[4:7], v[4:5], off
	v_or3_b32 v10, v12, v10, v11
	v_add_co_u32_e32 v86, vcc, s84, v84
	v_mad_u32_u24 v93, v10, s21, v33
	global_load_dwordx4 v[8:11], v[84:85], off
	v_addc_co_u32_e32 v87, vcc, 0, v85, vcc
	global_load_dwordx4 v[12:15], v[86:87], off
	s_add_u32 s14, s14, 0x4000
	s_addc_u32 s15, s15, 0
	v_mad_u64_u32 v[82:83], s[18:19], v16, s36, v[128:129]
	v_lshl_add_u64 v[88:89], s[14:15], 0, v[18:19]
	v_lshl_add_u64 v[90:91], s[14:15], 0, v[20:21]
	v_add_u32_e32 v94, 0x11800, v82
	s_waitcnt vmcnt(3)
	ds_write_b128 v81, v[0:3]
	s_waitcnt vmcnt(2)
	ds_write_b128 v92, v[4:7]
	s_waitcnt vmcnt(1)
	ds_write_b128 v82, v[8:11] offset:18432
	s_waitcnt vmcnt(0)
	ds_write_b128 v82, v[12:15] offset:27136
	global_load_dwordx4 v[0:3], v[88:89], off
	global_load_dwordx4 v[4:7], v[90:91], off
	global_load_dwordx4 v[8:11], v[84:85], off offset:256
	global_load_dwordx4 v[12:15], v[86:87], off offset:256
	s_waitcnt vmcnt(3)
	ds_write_b128 v81, v[0:3] offset:35840
	s_waitcnt vmcnt(2)
	ds_write_b128 v92, v[4:7] offset:35840
	s_waitcnt vmcnt(1)
	ds_write_b128 v82, v[8:11] offset:54272
	s_waitcnt vmcnt(0)
	ds_write_b128 v82, v[12:15] offset:62976
	s_waitcnt lgkmcnt(0)
	s_barrier
	ds_read_b128 v[0:3], v93
	ds_read_b128 v[16:19], v93 offset:32
	ds_read_b128 v[20:23], v93 offset:64
	ds_read_b128 v[24:27], v93 offset:96
	global_load_dwordx4 v[64:67], v[88:89], off
	global_load_dwordx4 v[72:75], v[90:91], off
	global_load_dwordx4 v[68:71], v[84:85], off offset:256
	global_load_dwordx4 v[76:79], v[86:87], off offset:256
	s_waitcnt lgkmcnt(3)
	v_mfma_f32_32x32x16_bf16 v[0:15], v[0:3], v[60:63], 0
	s_waitcnt lgkmcnt(2)
	v_mfma_f32_32x32x16_bf16 v[0:15], v[16:19], v[56:59], v[0:15]
	s_waitcnt lgkmcnt(1)
	v_mfma_f32_32x32x16_bf16 v[0:15], v[20:23], v[52:55], v[0:15]
	s_waitcnt lgkmcnt(0)
	v_mfma_f32_32x32x16_bf16 v[0:15], v[24:27], v[48:51], v[0:15]
	ds_read_b128 v[16:19], v93 offset:4608
	ds_read_b128 v[20:23], v93 offset:4640
	ds_read_b128 v[24:27], v93 offset:4672
	ds_read_b128 v[28:31], v93 offset:4704
	s_nop 7
	v_exp_f32_e32 v0, v0
	v_exp_f32_e32 v1, v1
	v_exp_f32_e32 v2, v2
	v_exp_f32_e32 v3, v3
	v_add_f32_e32 v34, 0, v0
	v_exp_f32_e32 v4, v4
	v_add_f32_e32 v34, v1, v34
	v_exp_f32_e32 v5, v5
	v_add_f32_e32 v34, v2, v34
	v_exp_f32_e32 v6, v6
	v_add_f32_e32 v34, v3, v34
	v_exp_f32_e32 v7, v7
	v_add_f32_e32 v34, v4, v34
	v_exp_f32_e32 v8, v8
	v_add_f32_e32 v34, v5, v34
	v_exp_f32_e32 v9, v9
	v_add_f32_e32 v34, v6, v34
	v_exp_f32_e32 v10, v10
	v_add_f32_e32 v34, v7, v34
	v_exp_f32_e32 v11, v11
	v_add_f32_e32 v34, v8, v34
	v_exp_f32_e32 v12, v12
	v_add_f32_e32 v34, v9, v34
	v_exp_f32_e32 v13, v13
	v_add_f32_e32 v34, v10, v34
	v_exp_f32_e32 v14, v14
	v_add_f32_e32 v34, v11, v34
	v_exp_f32_e32 v15, v15
	v_add_f32_e32 v34, v12, v34
	v_add_f32_e32 v34, v13, v34
	v_add_f32_e32 v34, v14, v34
	v_add_f32_e32 v34, v15, v34
	v_cvt_pk_bf16_f32 v96, v0, v1
	v_cvt_pk_bf16_f32 v100, v8, v9
	v_cvt_pk_bf16_f32 v97, v2, v3
	v_cvt_pk_bf16_f32 v101, v10, v11
	v_cvt_pk_bf16_f32 v98, v4, v5
	v_cvt_pk_bf16_f32 v102, v12, v13
	v_cvt_pk_bf16_f32 v99, v6, v7
	v_cvt_pk_bf16_f32 v103, v14, v15
	s_waitcnt lgkmcnt(3)
	v_mfma_f32_32x32x16_bf16 v[0:15], v[16:19], v[60:63], 0
	s_waitcnt lgkmcnt(2)
	v_mfma_f32_32x32x16_bf16 v[0:15], v[20:23], v[56:59], v[0:15]
	s_waitcnt lgkmcnt(1)
	v_mfma_f32_32x32x16_bf16 v[0:15], v[24:27], v[52:55], v[0:15]
	s_waitcnt lgkmcnt(0)
; #define KLOAD(kf_, base)                                                                       \
;   { _Pragma("unroll") for (int ks = 0; ks < NKS; ks++) kf_[ks] = *(const bf16x8*)((base) + kfo + ks * 32); }
; #define VLOAD(vf_, base)                                                                       \
;   { _Pragma("unroll") for (int q = 0; q < 4; q++) vf_[q] = *(const bf16x8*)((base) + vfo + (q >> 1) * 32 * VROW + (q & 1) * 32); }
; #define QKM(dst, kf_)                                                                          \
;   {                                                                                            \
;     _Pragma("unroll") for (int i = 0; i < 16; i++) dst[i] = 0.f;                               \
;     _Pragma("unroll") for (int ks = 0; ks < NKS; ks++) dst = MFMA(kf_[ks], qf[ks], dst);       \
;   }
; #define SB() __builtin_amdgcn_sched_barrier(0)
; template <int DK>
; DI void attn_core(const bf16x8 (&qf)[DK / 16], const short* Kg, const short* VTg, size_t ldvt, int ntiles, char* smem,
;                   f32x16 (&O)[2], float& lsum) {
;     ...
;   for (int t = 0; t < ntiles; t++) {
;     const int tn = t + 2 < ntiles ? t + 2 : ntiles - 1;
;     AGLOAD(tn);
;     const char* cur = smem + sc * ST;
;     const char* nxt = smem + sn * ST;
;     f32x16 Sn;
;     bf16x8 pa, pb, qa, qb;
;     bf16x8 kf[NKS], vf[4];
;     KLOAD(kf, cur + 32 * KROW);
;     SB();
;     SOFTMAX(Sc, pa, pb, l0);
;     SB();
;     QKM(Sn, kf);
;     SB();
;     KLOAD(kf, cur + 64 * KROW);
;     VLOAD(vf, cur);
;     SB();
;     SOFTMAX(Sn, qa, qb, l0);
;     SB();
;     QKM(Sc, kf);
;     PVM(vf, pa, pb);
;     SB();
;     KLOAD(kf, cur + 96 * KROW);
;     VLOAD(vf, cur + 64);
;     SB();
;     SOFTMAX(Sc, pa, pb, l0);
;     SB();
;     QKM(Sn, kf);
;     PVM(vf, qa, qb);
;     SB();
;     KLOAD(kf, nxt);
;     VLOAD(vf, cur + 128);
;     SB();
;     SOFTMAX(Sn, qa, qb, l0);
;     SB();
;     QKM(Sc, kf);
;     PVM(vf, pa, pb);
;     SB();
;     VLOAD(vf, cur + 192);
;     PVM(vf, qa, qb);
;     ASTORE(sw);
;     __syncthreads();
	v_mfma_f32_32x32x16_bf16 v[0:15], v[28:31], v[48:51], v[0:15]
	v_mad_u32_u24 v83, v32, s36, v33
	ds_read_b128 v[16:19], v93 offset:9216
	ds_read_b128 v[20:23], v93 offset:9248
	ds_read_b128 v[24:27], v93 offset:9280
	ds_read_b128 v[28:31], v93 offset:9312
	ds_read_b128 v[104:107], v83 offset:18432
	ds_read_b128 v[108:111], v83 offset:18464
	ds_read_b128 v[112:115], v83 offset:27136
	ds_read_b128 v[116:119], v83 offset:27168
	s_nop 2
	v_exp_f32_e32 v0, v0
	v_exp_f32_e32 v1, v1
	v_exp_f32_e32 v2, v2
	v_exp_f32_e32 v3, v3
	v_add_f32_e32 v32, v0, v34
	v_exp_f32_e32 v4, v4
	v_add_f32_e32 v32, v1, v32
	v_exp_f32_e32 v5, v5
	v_add_f32_e32 v32, v2, v32
	v_exp_f32_e32 v6, v6
	v_add_f32_e32 v32, v3, v32
	v_exp_f32_e32 v7, v7
	v_add_f32_e32 v32, v4, v32
	v_exp_f32_e32 v8, v8
	v_add_f32_e32 v32, v5, v32
	v_exp_f32_e32 v9, v9
	v_add_f32_e32 v32, v6, v32
	v_exp_f32_e32 v10, v10
	v_add_f32_e32 v32, v7, v32
	v_exp_f32_e32 v11, v11
	v_add_f32_e32 v32, v8, v32
	v_exp_f32_e32 v12, v12
	v_add_f32_e32 v32, v9, v32
	v_exp_f32_e32 v13, v13
	v_add_f32_e32 v32, v10, v32
	v_exp_f32_e32 v14, v14
	v_add_f32_e32 v32, v11, v32
	v_exp_f32_e32 v15, v15
	v_add_f32_e32 v32, v12, v32
	v_add_f32_e32 v32, v13, v32
	v_add_f32_e32 v32, v14, v32
	v_add_f32_e32 v95, v15, v32
	v_cvt_pk_bf16_f32 v120, v0, v1
	v_cvt_pk_bf16_f32 v124, v8, v9
	v_cvt_pk_bf16_f32 v121, v2, v3
	v_cvt_pk_bf16_f32 v125, v10, v11
	v_cvt_pk_bf16_f32 v122, v4, v5
	v_cvt_pk_bf16_f32 v126, v12, v13
	v_cvt_pk_bf16_f32 v123, v6, v7
	v_cvt_pk_bf16_f32 v127, v14, v15
	s_waitcnt lgkmcnt(7)
	v_mfma_f32_32x32x16_bf16 v[32:47], v[16:19], v[60:63], 0
	s_waitcnt lgkmcnt(6)
	v_mfma_f32_32x32x16_bf16 v[32:47], v[20:23], v[56:59], v[32:47]
	s_waitcnt lgkmcnt(5)
	v_mfma_f32_32x32x16_bf16 v[32:47], v[24:27], v[52:55], v[32:47]
	s_waitcnt lgkmcnt(4)
	v_mfma_f32_32x32x16_bf16 v[32:47], v[28:31], v[48:51], v[32:47]
	s_waitcnt lgkmcnt(3)
	v_mfma_f32_32x32x16_bf16 v[16:31], v[104:107], v[96:99], 0
	s_waitcnt lgkmcnt(1)
	v_mfma_f32_32x32x16_bf16 v[0:15], v[112:115], v[96:99], 0
	v_mfma_f32_32x32x16_bf16 v[16:31], v[108:111], v[100:103], v[16:31]
	s_waitcnt lgkmcnt(0)
	v_mfma_f32_32x32x16_bf16 v[0:15], v[116:119], v[100:103], v[0:15]
	ds_read_b128 v[96:99], v93 offset:13824
	ds_read_b128 v[100:103], v93 offset:13856
	ds_read_b128 v[104:107], v93 offset:13888
	ds_read_b128 v[108:111], v93 offset:13920
	ds_read_b128 v[112:115], v83 offset:18496
	ds_read_b128 v[116:119], v83 offset:18528
	ds_read_b128 v[130:133], v83 offset:27200
	ds_read_b128 v[134:137], v83 offset:27232
	v_exp_f32_e32 v32, v32
	v_exp_f32_e32 v33, v33
	v_exp_f32_e32 v34, v34
	v_exp_f32_e32 v35, v35
	v_add_f32_e32 v95, v32, v95
	v_exp_f32_e32 v36, v36
	v_add_f32_e32 v95, v33, v95
	v_exp_f32_e32 v37, v37
	v_add_f32_e32 v95, v34, v95
	v_exp_f32_e32 v38, v38
	v_add_f32_e32 v95, v35, v95
	v_exp_f32_e32 v39, v39
	v_add_f32_e32 v95, v36, v95
	v_exp_f32_e32 v40, v40
	v_add_f32_e32 v95, v37, v95
	v_exp_f32_e32 v41, v41
	v_add_f32_e32 v95, v38, v95
	v_exp_f32_e32 v42, v42
	v_add_f32_e32 v95, v39, v95
	v_exp_f32_e32 v43, v43
	v_add_f32_e32 v95, v40, v95
	v_exp_f32_e32 v44, v44
	v_add_f32_e32 v95, v41, v95
	v_exp_f32_e32 v45, v45
	v_add_f32_e32 v95, v42, v95
	v_exp_f32_e32 v46, v46
	v_add_f32_e32 v95, v43, v95
	v_exp_f32_e32 v47, v47
	v_add_f32_e32 v95, v44, v95
	v_add_f32_e32 v95, v45, v95
	v_add_f32_e32 v95, v46, v95
	v_add_f32_e32 v95, v47, v95
	v_cvt_pk_bf16_f32 v138, v32, v33
	v_cvt_pk_bf16_f32 v142, v40, v41
	v_cvt_pk_bf16_f32 v139, v34, v35
	v_cvt_pk_bf16_f32 v143, v42, v43
	v_cvt_pk_bf16_f32 v140, v36, v37
	v_cvt_pk_bf16_f32 v144, v44, v45
	v_cvt_pk_bf16_f32 v141, v38, v39
	v_cvt_pk_bf16_f32 v145, v46, v47
	s_waitcnt lgkmcnt(3)
	v_mfma_f32_32x32x16_bf16 v[16:31], v[112:115], v[120:123], v[16:31]
	s_waitcnt lgkmcnt(1)
	v_mfma_f32_32x32x16_bf16 v[0:15], v[130:133], v[120:123], v[0:15]
	v_mfma_f32_32x32x16_bf16 v[16:31], v[116:119], v[124:127], v[16:31]
	s_waitcnt lgkmcnt(0)
	v_mfma_f32_32x32x16_bf16 v[0:15], v[134:137], v[124:127], v[0:15]
	v_mfma_f32_32x32x16_bf16 v[32:47], v[96:99], v[60:63], 0
	v_mfma_f32_32x32x16_bf16 v[32:47], v[100:103], v[56:59], v[32:47]
	v_mfma_f32_32x32x16_bf16 v[32:47], v[104:107], v[52:55], v[32:47]
	ds_read_b128 v[96:99], v93 offset:35840
	ds_read_b128 v[100:103], v93 offset:35872
	ds_read_b128 v[104:107], v93 offset:35904
	ds_read_b128 v[112:115], v93 offset:35936
	ds_read_b128 v[116:119], v83 offset:18560
	ds_read_b128 v[120:123], v83 offset:18592
	ds_read_b128 v[124:127], v83 offset:27264
	ds_read_b128 v[130:133], v83 offset:27296
	v_mfma_f32_32x32x16_bf16 v[32:47], v[108:111], v[48:51], v[32:47]
	s_nop 11
	v_exp_f32_e32 v108, v32
	v_exp_f32_e32 v109, v33
	v_exp_f32_e32 v110, v34
	v_exp_f32_e32 v111, v35
	v_exp_f32_e32 v128, v36
	v_add_f32_e32 v95, v95, v108
	v_exp_f32_e32 v134, v37
	v_add_f32_e32 v95, v109, v95
	v_exp_f32_e32 v135, v38
	v_add_f32_e32 v95, v110, v95
	v_exp_f32_e32 v136, v39
	v_add_f32_e32 v95, v111, v95
	v_exp_f32_e32 v40, v40
	v_exp_f32_e32 v41, v41
	v_add_f32_e32 v95, v128, v95
	v_add_f32_e32 v95, v134, v95
	v_exp_f32_e32 v42, v42
	v_add_f32_e32 v95, v135, v95
	v_exp_f32_e32 v43, v43
	v_add_f32_e32 v95, v136, v95
	v_exp_f32_e32 v44, v44
	v_cvt_pk_bf16_f32 v36, v40, v41
	v_add_f32_e32 v40, v40, v95
	v_exp_f32_e32 v45, v45
	v_add_f32_e32 v40, v41, v40
	v_exp_f32_e32 v46, v46
	v_add_f32_e32 v40, v42, v40
	v_exp_f32_e32 v47, v47
	v_add_f32_e32 v40, v43, v40
	v_add_f32_e32 v40, v44, v40
	v_add_f32_e32 v40, v45, v40
	v_add_f32_e32 v40, v46, v40
	v_cvt_pk_bf16_f32 v32, v108, v109
	v_cvt_pk_bf16_f32 v33, v110, v111
	v_cvt_pk_bf16_f32 v37, v42, v43
	v_cvt_pk_bf16_f32 v34, v128, v134
	v_cvt_pk_bf16_f32 v38, v44, v45
	v_cvt_pk_bf16_f32 v35, v135, v136
	v_cvt_pk_bf16_f32 v39, v46, v47
	v_add_f32_e32 v108, v47, v40
	s_waitcnt lgkmcnt(3)
	v_mfma_f32_32x32x16_bf16 v[16:31], v[116:119], v[138:141], v[16:31]
	s_waitcnt lgkmcnt(1)
	v_mfma_f32_32x32x16_bf16 v[0:15], v[124:127], v[138:141], v[0:15]
	v_mfma_f32_32x32x16_bf16 v[16:31], v[120:123], v[142:145], v[16:31]
	s_waitcnt lgkmcnt(0)
	v_mfma_f32_32x32x16_bf16 v[0:15], v[130:133], v[142:145], v[0:15]
	ds_read_b128 v[40:43], v83 offset:18624
	v_add_u32_e32 v95, 0x11800, v81
	s_waitcnt lgkmcnt(0)
	v_mfma_f32_32x32x16_bf16 v[16:31], v[40:43], v[32:35], v[16:31]
	ds_read_b128 v[40:43], v83 offset:27328
	s_waitcnt lgkmcnt(0)
	v_mfma_f32_32x32x16_bf16 v[0:15], v[40:43], v[32:35], v[0:15]
	ds_read_b128 v[32:35], v83 offset:18656
	s_waitcnt lgkmcnt(0)
	v_mfma_f32_32x32x16_bf16 v[16:31], v[32:35], v[36:39], v[16:31]
	ds_read_b128 v[32:35], v83 offset:27360
	s_waitcnt vmcnt(3)
	ds_write_b128 v95, v[64:67]
	v_add_u32_e32 v64, 0x11800, v92
	s_waitcnt vmcnt(2)
	ds_write_b128 v64, v[72:75]
	s_waitcnt vmcnt(1)
	ds_write_b128 v94, v[68:71] offset:18432
	s_waitcnt vmcnt(0)
	ds_write_b128 v94, v[76:79] offset:27136
	s_waitcnt lgkmcnt(0)
	s_barrier
; #define KLOAD(kf_, base)                                                                       \
;   { _Pragma("unroll") for (int ks = 0; ks < NKS; ks++) kf_[ks] = *(const bf16x8*)((base) + kfo + ks * 32); }
; #define VLOAD(vf_, base)                                                                       \
;   { _Pragma("unroll") for (int q = 0; q < 4; q++) vf_[q] = *(const bf16x8*)((base) + vfo + (q >> 1) * 32 * VROW + (q & 1) * 32); }
; #define QKM(dst, kf_)                                                                          \
;   {                                                                                            \
;     _Pragma("unroll") for (int i = 0; i < 16; i++) dst[i] = 0.f;                               \
;     _Pragma("unroll") for (int ks = 0; ks < NKS; ks++) dst = MFMA(kf_[ks], qf[ks], dst);       \
;   }
; #define SB() __builtin_amdgcn_sched_barrier(0)
; template <int DK>
; DI void attn_core(const bf16x8 (&qf)[DK / 16], const short* Kg, const short* VTg, size_t ldvt, int ntiles, char* smem,
;                   f32x16 (&O)[2], float& lsum) {
;     ...
;   for (int t = 0; t < ntiles; t++) {
;     const int tn = t + 2 < ntiles ? t + 2 : ntiles - 1;
;     AGLOAD(tn);
;     const char* cur = smem + sc * ST;
;     const char* nxt = smem + sn * ST;
;     f32x16 Sn;
;     bf16x8 pa, pb, qa, qb;
;     bf16x8 kf[NKS], vf[4];
;     KLOAD(kf, cur + 32 * KROW);
;     SB();
;     SOFTMAX(Sc, pa, pb, l0);
;     SB();
;     QKM(Sn, kf);
;     SB();
;     KLOAD(kf, cur + 64 * KROW);
;     VLOAD(vf, cur);
;     SB();
;     SOFTMAX(Sn, qa, qb, l0);
;     SB();
;     QKM(Sc, kf);
;     PVM(vf, pa, pb);
;     SB();
;     KLOAD(kf, cur + 96 * KROW);
;     VLOAD(vf, cur + 64);
;     SB();
;     SOFTMAX(Sc, pa, pb, l0);
;     SB();
;     QKM(Sn, kf);
;     PVM(vf, qa, qb);
;     SB();
;     KLOAD(kf, nxt);
;     VLOAD(vf, cur + 128);
;     SB();
;     SOFTMAX(Sn, qa, qb, l0);
;     SB();
;     QKM(Sc, kf);
;     PVM(vf, pa, pb);
;     SB();
;     VLOAD(vf, cur + 192);
;     PVM(vf, qa, qb);
;     ASTORE(sw);
;     __syncthreads();
	global_load_dwordx4 v[68:71], v[90:91], off
	global_load_dwordx4 v[64:67], v[84:85], off offset:256
	global_load_dwordx4 v[76:79], v[88:89], off
	global_load_dwordx4 v[72:75], v[86:87], off offset:256
	v_mfma_f32_32x32x16_bf16 v[0:15], v[32:35], v[36:39], v[0:15]
	v_mfma_f32_32x32x16_bf16 v[32:47], v[96:99], v[60:63], 0
	v_mfma_f32_32x32x16_bf16 v[32:47], v[100:103], v[56:59], v[32:47]
	ds_read_b128 v[84:87], v93 offset:40448
	ds_read_b128 v[88:91], v93 offset:40480
	ds_read_b128 v[94:97], v93 offset:40512
	ds_read_b128 v[98:101], v93 offset:40544
	v_mfma_f32_32x32x16_bf16 v[32:47], v[104:107], v[52:55], v[32:47]
	v_mfma_f32_32x32x16_bf16 v[32:47], v[112:115], v[48:51], v[32:47]
	s_nop 11
	v_exp_f32_e32 v32, v32
	v_exp_f32_e32 v33, v33
	v_exp_f32_e32 v34, v34
	v_exp_f32_e32 v35, v35
	v_add_f32_e32 v102, v108, v32
	v_exp_f32_e32 v36, v36
	v_add_f32_e32 v102, v33, v102
	v_exp_f32_e32 v37, v37
	v_add_f32_e32 v102, v34, v102
	v_exp_f32_e32 v38, v38
	v_add_f32_e32 v102, v35, v102
	v_exp_f32_e32 v39, v39
	v_add_f32_e32 v102, v36, v102
	v_exp_f32_e32 v40, v40
	v_add_f32_e32 v102, v37, v102
	v_exp_f32_e32 v41, v41
	v_add_f32_e32 v102, v38, v102
	v_exp_f32_e32 v42, v42
	v_add_f32_e32 v102, v39, v102
	v_exp_f32_e32 v43, v43
	v_add_f32_e32 v102, v40, v102
	v_exp_f32_e32 v44, v44
	v_add_f32_e32 v102, v41, v102
	v_exp_f32_e32 v45, v45
	v_add_f32_e32 v102, v42, v102
	v_exp_f32_e32 v46, v46
	v_add_f32_e32 v102, v43, v102
	v_exp_f32_e32 v47, v47
	v_add_f32_e32 v102, v44, v102
	v_add_f32_e32 v102, v45, v102
	v_add_f32_e32 v102, v46, v102
	v_add_f32_e32 v126, v47, v102
	v_cvt_pk_bf16_f32 v102, v32, v33
	v_cvt_pk_bf16_f32 v106, v40, v41
	v_cvt_pk_bf16_f32 v103, v34, v35
	v_cvt_pk_bf16_f32 v107, v42, v43
	v_cvt_pk_bf16_f32 v104, v36, v37
	v_cvt_pk_bf16_f32 v108, v44, v45
	v_cvt_pk_bf16_f32 v105, v38, v39
	v_cvt_pk_bf16_f32 v109, v46, v47
	s_waitcnt lgkmcnt(3)
	v_mfma_f32_32x32x16_bf16 v[32:47], v[84:87], v[60:63], 0
	s_waitcnt lgkmcnt(2)
	v_mfma_f32_32x32x16_bf16 v[32:47], v[88:91], v[56:59], v[32:47]
	s_waitcnt lgkmcnt(1)
	v_mfma_f32_32x32x16_bf16 v[32:47], v[94:97], v[52:55], v[32:47]
	s_waitcnt lgkmcnt(0)
	v_mfma_f32_32x32x16_bf16 v[32:47], v[98:101], v[48:51], v[32:47]
	ds_read_b128 v[84:87], v93 offset:45056
	ds_read_b128 v[88:91], v93 offset:45088
	ds_read_b128 v[94:97], v93 offset:45120
	ds_read_b128 v[98:101], v93 offset:45152
	ds_read_b128 v[110:113], v83 offset:54272
	ds_read_b128 v[114:117], v83 offset:54304
	ds_read_b128 v[118:121], v83 offset:62976
	ds_read_b128 v[122:125], v83 offset:63008
	s_nop 3
	v_exp_f32_e32 v32, v32
	v_exp_f32_e32 v33, v33
	v_exp_f32_e32 v34, v34
	v_exp_f32_e32 v35, v35
	v_add_f32_e32 v126, v126, v32
	v_exp_f32_e32 v36, v36
	v_add_f32_e32 v126, v33, v126
	v_exp_f32_e32 v37, v37
	v_add_f32_e32 v126, v34, v126
	v_exp_f32_e32 v38, v38
	v_add_f32_e32 v126, v35, v126
	v_exp_f32_e32 v39, v39
	v_add_f32_e32 v126, v36, v126
	v_exp_f32_e32 v40, v40
	v_add_f32_e32 v126, v37, v126
	v_exp_f32_e32 v41, v41
	v_add_f32_e32 v126, v38, v126
	v_exp_f32_e32 v42, v42
	v_add_f32_e32 v126, v39, v126
	v_exp_f32_e32 v43, v43
	v_add_f32_e32 v126, v40, v126
	v_exp_f32_e32 v44, v44
	v_add_f32_e32 v126, v41, v126
	v_exp_f32_e32 v45, v45
	v_add_f32_e32 v126, v42, v126
	v_exp_f32_e32 v46, v46
	v_add_f32_e32 v126, v43, v126
	v_exp_f32_e32 v47, v47
	v_add_f32_e32 v126, v44, v126
	v_add_f32_e32 v126, v45, v126
	v_add_f32_e32 v126, v46, v126
	v_add_f32_e32 v126, v47, v126
	v_cvt_pk_bf16_f32 v130, v32, v33
	v_cvt_pk_bf16_f32 v134, v40, v41
	v_cvt_pk_bf16_f32 v131, v34, v35
	v_cvt_pk_bf16_f32 v135, v42, v43
	v_cvt_pk_bf16_f32 v132, v36, v37
	v_cvt_pk_bf16_f32 v136, v44, v45
	v_cvt_pk_bf16_f32 v133, v38, v39
	v_cvt_pk_bf16_f32 v137, v46, v47
	s_waitcnt lgkmcnt(7)
	v_mfma_f32_32x32x16_bf16 v[32:47], v[84:87], v[60:63], 0
	s_waitcnt lgkmcnt(6)
	v_mfma_f32_32x32x16_bf16 v[32:47], v[88:91], v[56:59], v[32:47]
	s_waitcnt lgkmcnt(5)
	v_mfma_f32_32x32x16_bf16 v[32:47], v[94:97], v[52:55], v[32:47]
	s_waitcnt lgkmcnt(3)
	v_mfma_f32_32x32x16_bf16 v[16:31], v[110:113], v[102:105], v[16:31]
	s_waitcnt lgkmcnt(1)
	v_mfma_f32_32x32x16_bf16 v[0:15], v[118:121], v[102:105], v[0:15]
	v_mfma_f32_32x32x16_bf16 v[32:47], v[98:101], v[48:51], v[32:47]
	v_mfma_f32_32x32x16_bf16 v[16:31], v[114:117], v[106:109], v[16:31]
	s_waitcnt lgkmcnt(0)
	v_mfma_f32_32x32x16_bf16 v[0:15], v[122:125], v[106:109], v[0:15]
	ds_read_b128 v[84:87], v93 offset:49664
	ds_read_b128 v[88:91], v93 offset:49696
	ds_read_b128 v[94:97], v93 offset:49728
	ds_read_b128 v[98:101], v93 offset:49760
	ds_read_b128 v[102:105], v83 offset:54336
	ds_read_b128 v[106:109], v83 offset:54368
	ds_read_b128 v[110:113], v83 offset:63040
	ds_read_b128 v[114:117], v83 offset:63072
	s_nop 0
	v_exp_f32_e32 v32, v32
	v_exp_f32_e32 v33, v33
	v_exp_f32_e32 v34, v34
	v_exp_f32_e32 v35, v35
	v_add_f32_e32 v93, v32, v126
	v_exp_f32_e32 v36, v36
	v_add_f32_e32 v93, v33, v93
	v_exp_f32_e32 v37, v37
	v_add_f32_e32 v93, v34, v93
	v_exp_f32_e32 v38, v38
	v_add_f32_e32 v93, v35, v93
	v_exp_f32_e32 v39, v39
	v_add_f32_e32 v93, v36, v93
	v_exp_f32_e32 v40, v40
	v_add_f32_e32 v93, v37, v93
	v_exp_f32_e32 v41, v41
	v_add_f32_e32 v93, v38, v93
	v_exp_f32_e32 v42, v42
	v_add_f32_e32 v93, v39, v93
	v_exp_f32_e32 v43, v43
	v_add_f32_e32 v93, v40, v93
	v_exp_f32_e32 v44, v44
	v_add_f32_e32 v93, v41, v93
	v_exp_f32_e32 v45, v45
	v_add_f32_e32 v93, v42, v93
	v_exp_f32_e32 v46, v46
	v_add_f32_e32 v93, v43, v93
	v_exp_f32_e32 v47, v47
	v_add_f32_e32 v93, v44, v93
	v_add_f32_e32 v93, v45, v93
	v_add_f32_e32 v93, v46, v93
	v_add_f32_e32 v93, v47, v93
	v_cvt_pk_bf16_f32 v118, v32, v33
	v_cvt_pk_bf16_f32 v122, v40, v41
	v_cvt_pk_bf16_f32 v119, v34, v35
	v_cvt_pk_bf16_f32 v123, v42, v43
	v_cvt_pk_bf16_f32 v120, v36, v37
	v_cvt_pk_bf16_f32 v124, v44, v45
	v_cvt_pk_bf16_f32 v121, v38, v39
	v_cvt_pk_bf16_f32 v125, v46, v47
	s_waitcnt lgkmcnt(3)
; #define KLOAD(kf_, base)                                                                       \
;   { _Pragma("unroll") for (int ks = 0; ks < NKS; ks++) kf_[ks] = *(const bf16x8*)((base) + kfo + ks * 32); }
; #define VLOAD(vf_, base)                                                                       \
;   { _Pragma("unroll") for (int q = 0; q < 4; q++) vf_[q] = *(const bf16x8*)((base) + vfo + (q >> 1) * 32 * VROW + (q & 1) * 32); }
; #define QKM(dst, kf_)                                                                          \
;   {                                                                                            \
;     _Pragma("unroll") for (int i = 0; i < 16; i++) dst[i] = 0.f;                               \
;     _Pragma("unroll") for (int ks = 0; ks < NKS; ks++) dst = MFMA(kf_[ks], qf[ks], dst);       \
;   }
; #define SB() __builtin_amdgcn_sched_barrier(0)
; template <int DK>
; DI void attn_core(const bf16x8 (&qf)[DK / 16], const short* Kg, const short* VTg, size_t ldvt, int ntiles, char* smem,
;                   f32x16 (&O)[2], float& lsum) {
;     ...
;   for (int t = 0; t < ntiles; t++) {
;     const int tn = t + 2 < ntiles ? t + 2 : ntiles - 1;
;     AGLOAD(tn);
;     const char* cur = smem + sc * ST;
;     const char* nxt = smem + sn * ST;
;     f32x16 Sn;
;     bf16x8 pa, pb, qa, qb;
;     bf16x8 kf[NKS], vf[4];
;     KLOAD(kf, cur + 32 * KROW);
;     SB();
;     SOFTMAX(Sc, pa, pb, l0);
;     SB();
;     QKM(Sn, kf);
;     SB();
;     KLOAD(kf, cur + 64 * KROW);
;     VLOAD(vf, cur);
;     SB();
;     SOFTMAX(Sn, qa, qb, l0);
;     SB();
;     QKM(Sc, kf);
;     PVM(vf, pa, pb);
;     SB();
;     KLOAD(kf, cur + 96 * KROW);
;     VLOAD(vf, cur + 64);
;     SB();
;     SOFTMAX(Sc, pa, pb, l0);
;     SB();
;     QKM(Sn, kf);
;     PVM(vf, qa, qb);
;     SB();
;     KLOAD(kf, nxt);
;     VLOAD(vf, cur + 128);
;     SB();
;     SOFTMAX(Sn, qa, qb, l0);
;     SB();
;     QKM(Sc, kf);
;     PVM(vf, pa, pb);
;     SB();
;     VLOAD(vf, cur + 192);
;     PVM(vf, qa, qb);
;     ASTORE(sw);
;     __syncthreads();
	v_mfma_f32_32x32x16_bf16 v[16:31], v[102:105], v[130:133], v[16:31]
	s_waitcnt lgkmcnt(1)
	v_mfma_f32_32x32x16_bf16 v[0:15], v[110:113], v[130:133], v[0:15]
	v_mfma_f32_32x32x16_bf16 v[16:31], v[106:109], v[134:137], v[16:31]
	s_waitcnt lgkmcnt(0)
	v_mfma_f32_32x32x16_bf16 v[0:15], v[114:117], v[134:137], v[0:15]
	v_mfma_f32_32x32x16_bf16 v[32:47], v[84:87], v[60:63], 0
	v_mfma_f32_32x32x16_bf16 v[32:47], v[88:91], v[56:59], v[32:47]
	v_mfma_f32_32x32x16_bf16 v[32:47], v[94:97], v[52:55], v[32:47]
	ds_read_b128 v[52:55], v83 offset:54400
	ds_read_b128 v[56:59], v83 offset:54432
	ds_read_b128 v[60:63], v83 offset:63104
	ds_read_b128 v[84:87], v83 offset:63136
	v_mfma_f32_32x32x16_bf16 v[32:47], v[98:101], v[48:51], v[32:47]
	s_nop 11
	v_exp_f32_e32 v48, v32
	v_exp_f32_e32 v49, v33
	v_exp_f32_e32 v50, v34
	v_exp_f32_e32 v51, v35
	v_exp_f32_e32 v88, v36
	v_cvt_pk_bf16_f32 v32, v48, v49
	v_add_f32_e32 v48, v93, v48
	v_exp_f32_e32 v89, v37
	v_add_f32_e32 v48, v49, v48
	v_exp_f32_e32 v90, v38
	v_add_f32_e32 v48, v50, v48
	v_exp_f32_e32 v91, v39
	v_add_f32_e32 v48, v51, v48
	v_exp_f32_e32 v40, v40
	v_exp_f32_e32 v41, v41
	v_add_f32_e32 v48, v88, v48
	v_add_f32_e32 v48, v89, v48
	v_exp_f32_e32 v42, v42
	v_add_f32_e32 v48, v90, v48
	v_exp_f32_e32 v43, v43
	v_add_f32_e32 v48, v91, v48
	v_exp_f32_e32 v44, v44
	v_cvt_pk_bf16_f32 v36, v40, v41
	v_add_f32_e32 v40, v40, v48
	v_exp_f32_e32 v45, v45
	v_add_f32_e32 v40, v41, v40
	v_exp_f32_e32 v46, v46
	v_add_f32_e32 v40, v42, v40
	v_exp_f32_e32 v47, v47
	v_add_f32_e32 v40, v43, v40
	v_add_f32_e32 v40, v44, v40
	v_add_f32_e32 v40, v45, v40
	v_add_f32_e32 v40, v46, v40
	v_cvt_pk_bf16_f32 v33, v50, v51
	v_cvt_pk_bf16_f32 v37, v42, v43
	v_cvt_pk_bf16_f32 v34, v88, v89
	v_cvt_pk_bf16_f32 v38, v44, v45
	v_cvt_pk_bf16_f32 v35, v90, v91
	v_cvt_pk_bf16_f32 v39, v46, v47
	v_add_f32_e32 v88, v47, v40
	s_waitcnt lgkmcnt(3)
	v_mfma_f32_32x32x16_bf16 v[16:31], v[52:55], v[118:121], v[16:31]
	s_waitcnt lgkmcnt(1)
	v_mfma_f32_32x32x16_bf16 v[0:15], v[60:63], v[118:121], v[0:15]
	v_mfma_f32_32x32x16_bf16 v[16:31], v[56:59], v[122:125], v[16:31]
	s_waitcnt lgkmcnt(0)
	v_mfma_f32_32x32x16_bf16 v[0:15], v[84:87], v[122:125], v[0:15]
	ds_read_b128 v[40:43], v83 offset:54464
	ds_read_b128 v[44:47], v83 offset:54496
	ds_read_b128 v[48:51], v83 offset:63168
	ds_read_b128 v[52:55], v83 offset:63200
	v_mov_b32_e32 v60, v196
	s_waitcnt vmcnt(1)
	ds_write_b128 v81, v[76:79]
	ds_write_b128 v92, v[68:71]
	ds_write_b128 v82, v[64:67] offset:18432
	s_waitcnt vmcnt(0)
	ds_write_b128 v82, v[72:75] offset:27136
	s_waitcnt lgkmcnt(0)
	s_barrier
; DI int my_tid() { int t = threadIdx.x; asm volatile("" : "+v"(t)); return t; }
; DI float bf_lo(unsigned u) { return __uint_as_float(u << 16); }
; DI float bf_hi(unsigned u) { return __uint_as_float(u & 0xffff0000u); }
; DI void attn_store(const f32x16 (&O)[2], float lsum, int tok, int col0, const short* gate, short* o, char* smem) {
;   const int tid = my_tid(), lane = tid & 63, w = tid >> 6, r = lane & 31, h = lane >> 5;
;   float l = lsum + __shfl_xor(lsum, 32);
;   float inv = __builtin_amdgcn_rcpf(l);
;   float* pw = (float*)(smem + w * (32 * 68 * 4));
;   const int tokw = tok - r;
;   const int ch = lane & 7;
;   u32x4 gpre[4];
; #pragma unroll
;   for (int j = 0; j < 4; j++) gpre[j] = *(const u32x4*)(gate + (size_t)(tokw + j * 8 + (lane >> 3)) * 1024 + col0 + ch * 8);
; #pragma unroll
;   for (int dt = 0; dt < 2; dt++)
; #pragma unroll
;     for (int q = 0; q < 4; q++) {
;       f32x4 t = {O[dt][q * 4 + 0] * inv, O[dt][q * 4 + 1] * inv, O[dt][q * 4 + 2] * inv, O[dt][q * 4 + 3] * inv};
;       *(f32x4*)(pw + r * 68 + dt * 32 + 8 * q + 4 * h) = t;
;     }
;   asm volatile("s_waitcnt lgkmcnt(0)" ::: "memory");
; #pragma unroll
;   for (int j = 0; j < 4; j++) {
;     const int row = j * 8 + (lane >> 3);
;     const size_t g = (size_t)(tokw + row) * 1024 + col0 + ch * 8;
;     const u32x4 gv = gpre[j];
;     const f32x4 a = *(const f32x4*)(pw + row * 68 + ch * 8), c = *(const f32x4*)(pw + row * 68 + ch * 8 + 4);
;     u32x4 ov;
;     ov[0] = pack_bf16(a[0] * bf_lo(gv[0]), a[1] * bf_hi(gv[0]));
;     ov[1] = pack_bf16(a[2] * bf_lo(gv[1]), a[3] * bf_hi(gv[1]));
;     ov[2] = pack_bf16(c[0] * bf_lo(gv[2]), c[1] * bf_hi(gv[2]));
;     ov[3] = pack_bf16(c[2] * bf_lo(gv[3]), c[3] * bf_hi(gv[3]));
;     __builtin_nontemporal_store(ov, (u32x4*)(o + g));
;   }
;   __syncthreads();
	v_mfma_f32_32x32x16_bf16 v[16:31], v[40:43], v[32:35], v[16:31]
	v_and_b32_e32 v61, 31, v60
	v_bfe_u32 v62, v60, 3, 3
	s_or_b32 s30, s30, 0x600
	s_add_i32 s16, s16, s51
	s_cmpk_gt_i32 s16, 0x4ff
	v_mfma_f32_32x32x16_bf16 v[0:15], v[48:51], v[32:35], v[0:15]
	v_sub_u32_e32 v32, v80, v61
	v_add_u32_e32 v48, v62, v32
	v_lshlrev_b32_e32 v32, 3, v60
	v_and_b32_e32 v63, 56, v32
	v_lshlrev_b32_e32 v128, 1, v63
	v_ashrrev_i32_e32 v49, 31, v48
	v_lshl_add_u64 v[50:51], s[6:7], 0, v[128:129]
	v_lshlrev_b64 v[56:57], 11, v[48:49]
	v_lshl_add_u64 v[32:33], v[50:51], 0, v[56:57]
	v_lshl_add_u64 v[32:33], v[32:33], 0, s[30:31]
	global_load_dwordx4 v[32:35], v[32:33], off
	v_add_u32_e32 v40, 8, v48
	v_ashrrev_i32_e32 v41, 31, v40
	v_lshlrev_b64 v[58:59], 11, v[40:41]
	v_lshl_add_u64 v[40:41], v[50:51], 0, v[58:59]
	v_lshl_add_u64 v[40:41], v[40:41], 0, s[30:31]
	global_load_dwordx4 v[40:43], v[40:41], off
	v_mfma_f32_32x32x16_bf16 v[16:31], v[44:47], v[36:39], v[16:31]
	v_and_b32_e32 v45, 64, v200
	v_xor_b32_e32 v44, 32, v200
	v_add_u32_e32 v45, 64, v45
	v_cmp_lt_i32_e32 vcc, v44, v45
	s_nop 1
	v_cndmask_b32_e32 v44, v200, v44, vcc
	v_mfma_f32_32x32x16_bf16 v[0:15], v[52:55], v[36:39], v[0:15]
	v_lshrrev_b32_e32 v36, 6, v60
	v_mul_lo_u32 v55, v36, s22
	v_add_u32_e32 v36, 16, v48
	v_ashrrev_i32_e32 v37, 31, v36
	v_lshlrev_b64 v[52:53], 11, v[36:37]
	v_lshl_add_u64 v[36:37], v[50:51], 0, v[52:53]
	v_lshl_add_u64 v[36:37], v[36:37], 0, s[30:31]
	v_lshlrev_b32_e32 v44, 2, v44
	global_load_dwordx4 v[36:39], v[36:37], off
	ds_bpermute_b32 v44, v44, v88
	s_waitcnt lgkmcnt(0)
	v_add_f32_e32 v54, v88, v44
	v_add_u32_e32 v44, 24, v48
	v_ashrrev_i32_e32 v45, 31, v44
	v_lshlrev_b64 v[48:49], 11, v[44:45]
	v_lshl_add_u64 v[44:45], v[50:51], 0, v[48:49]
	v_lshl_add_u64 v[44:45], v[44:45], 0, s[30:31]
	global_load_dwordx4 v[44:47], v[44:45], off
	v_rcp_f32_e32 v50, v54
	v_lshrrev_b32_e32 v54, 1, v60
	v_mul_u32_u24_e32 v51, 0x110, v61
	v_and_b32_e32 v54, 16, v54
	v_add3_u32 v51, v55, v51, v54
	v_pk_mul_f32 v[16:17], v[16:17], v[50:51] op_sel_hi:[1,0]
	v_pk_mul_f32 v[18:19], v[18:19], v[50:51] op_sel_hi:[1,0]
	v_pk_mul_f32 v[0:1], v[0:1], v[50:51] op_sel_hi:[1,0]
	v_pk_mul_f32 v[2:3], v[2:3], v[50:51] op_sel_hi:[1,0]
	ds_write_b128 v51, v[16:19]
	v_pk_mul_f32 v[16:17], v[20:21], v[50:51] op_sel_hi:[1,0]
	v_pk_mul_f32 v[18:19], v[22:23], v[50:51] op_sel_hi:[1,0]
	ds_write_b128 v51, v[0:3] offset:128
	v_pk_mul_f32 v[0:1], v[4:5], v[50:51] op_sel_hi:[1,0]
	v_pk_mul_f32 v[2:3], v[6:7], v[50:51] op_sel_hi:[1,0]
	ds_write_b128 v51, v[16:19] offset:32
	v_pk_mul_f32 v[16:17], v[24:25], v[50:51] op_sel_hi:[1,0]
	v_pk_mul_f32 v[18:19], v[26:27], v[50:51] op_sel_hi:[1,0]
	ds_write_b128 v51, v[0:3] offset:160
	v_pk_mul_f32 v[0:1], v[8:9], v[50:51] op_sel_hi:[1,0]
	v_pk_mul_f32 v[2:3], v[10:11], v[50:51] op_sel_hi:[1,0]
	ds_write_b128 v51, v[16:19] offset:64
	v_pk_mul_f32 v[16:17], v[28:29], v[50:51] op_sel_hi:[1,0]
	v_pk_mul_f32 v[18:19], v[30:31], v[50:51] op_sel_hi:[1,0]
	ds_write_b128 v51, v[0:3] offset:192
	v_pk_mul_f32 v[0:1], v[12:13], v[50:51] op_sel_hi:[1,0]
	v_pk_mul_f32 v[2:3], v[14:15], v[50:51] op_sel_hi:[1,0]
	ds_write_b128 v51, v[16:19] offset:96
	ds_write_b128 v51, v[0:3] offset:224
	v_lshl_or_b32 v0, v63, 2, v55
	s_waitcnt lgkmcnt(0)
	v_mad_u32_u24 v12, v62, s36, v0
	ds_read_b128 v[0:3], v12
	ds_read_b128 v[4:7], v12 offset:16
	v_lshl_add_u64 v[8:9], s[8:9], 0, v[128:129]
	s_waitcnt vmcnt(3)
	v_lshlrev_b32_e32 v10, 16, v32
	v_and_b32_e32 v11, 0xffff0000, v32
	s_waitcnt lgkmcnt(1)
	v_pk_mul_f32 v[0:1], v[0:1], v[10:11]
	v_lshlrev_b32_e32 v10, 16, v33
	v_and_b32_e32 v11, 0xffff0000, v33
	v_pk_mul_f32 v[2:3], v[2:3], v[10:11]
	v_cvt_pk_bf16_f32 v0, v0, v1
	v_cvt_pk_bf16_f32 v1, v2, v3
	v_lshlrev_b32_e32 v2, 16, v34
	v_and_b32_e32 v3, 0xffff0000, v34
	s_waitcnt lgkmcnt(0)
	v_pk_mul_f32 v[2:3], v[4:5], v[2:3]
	v_lshlrev_b32_e32 v4, 16, v35
	v_and_b32_e32 v5, 0xffff0000, v35
	v_pk_mul_f32 v[4:5], v[6:7], v[4:5]
	v_cvt_pk_bf16_f32 v2, v2, v3
	v_cvt_pk_bf16_f32 v3, v4, v5
	v_lshl_add_u64 v[4:5], v[8:9], 0, v[56:57]
	v_lshl_add_u64 v[10:11], v[4:5], 0, s[30:31]
	ds_read_b128 v[4:7], v12 offset:2176
	global_store_dwordx4 v[10:11], v[0:3], off nt
	ds_read_b128 v[0:3], v12 offset:2192
	s_waitcnt vmcnt(3)
	v_lshlrev_b32_e32 v10, 16, v40
	v_and_b32_e32 v11, 0xffff0000, v40
	s_waitcnt lgkmcnt(1)
	v_pk_mul_f32 v[4:5], v[4:5], v[10:11]
	v_lshlrev_b32_e32 v10, 16, v41
	v_and_b32_e32 v11, 0xffff0000, v41
	v_pk_mul_f32 v[6:7], v[6:7], v[10:11]
	v_cvt_pk_bf16_f32 v4, v4, v5
	v_cvt_pk_bf16_f32 v5, v6, v7
	v_lshlrev_b32_e32 v6, 16, v42
	v_and_b32_e32 v7, 0xffff0000, v42
	s_waitcnt lgkmcnt(0)
	v_pk_mul_f32 v[0:1], v[0:1], v[6:7]
	s_nop 0
	v_cvt_pk_bf16_f32 v6, v0, v1
	v_lshlrev_b32_e32 v0, 16, v43
	v_and_b32_e32 v1, 0xffff0000, v43
	v_pk_mul_f32 v[0:1], v[2:3], v[0:1]
	s_nop 0
	v_cvt_pk_bf16_f32 v7, v0, v1
	v_lshl_add_u64 v[0:1], v[8:9], 0, v[58:59]
	v_lshl_add_u64 v[10:11], v[0:1], 0, s[30:31]
	ds_read_b128 v[0:3], v12 offset:4352
	global_store_dwordx4 v[10:11], v[4:7], off nt
	ds_read_b128 v[4:7], v12 offset:4368
	s_waitcnt vmcnt(3)
	v_lshlrev_b32_e32 v10, 16, v36
	v_and_b32_e32 v11, 0xffff0000, v36
	s_waitcnt lgkmcnt(1)
	v_pk_mul_f32 v[0:1], v[0:1], v[10:11]
	v_lshlrev_b32_e32 v10, 16, v37
	v_and_b32_e32 v11, 0xffff0000, v37
	v_pk_mul_f32 v[2:3], v[2:3], v[10:11]
	v_cvt_pk_bf16_f32 v0, v0, v1
	v_cvt_pk_bf16_f32 v1, v2, v3
	v_lshlrev_b32_e32 v2, 16, v38
	v_and_b32_e32 v3, 0xffff0000, v38
	s_waitcnt lgkmcnt(0)
	v_pk_mul_f32 v[2:3], v[4:5], v[2:3]
	v_lshlrev_b32_e32 v4, 16, v39
	v_and_b32_e32 v5, 0xffff0000, v39
	v_pk_mul_f32 v[4:5], v[6:7], v[4:5]
	v_cvt_pk_bf16_f32 v2, v2, v3
	v_cvt_pk_bf16_f32 v3, v4, v5
	v_lshl_add_u64 v[4:5], v[8:9], 0, v[52:53]
	v_lshl_add_u64 v[10:11], v[4:5], 0, s[30:31]
	ds_read_b128 v[4:7], v12 offset:6528
	global_store_dwordx4 v[10:11], v[0:3], off nt
	ds_read_b128 v[0:3], v12 offset:6544
	s_waitcnt vmcnt(3)
	v_lshlrev_b32_e32 v10, 16, v44
	v_and_b32_e32 v11, 0xffff0000, v44
	s_waitcnt lgkmcnt(1)
	v_pk_mul_f32 v[4:5], v[4:5], v[10:11]
	v_lshlrev_b32_e32 v10, 16, v45
	v_and_b32_e32 v11, 0xffff0000, v45
	v_pk_mul_f32 v[6:7], v[6:7], v[10:11]
	v_cvt_pk_bf16_f32 v4, v4, v5
	v_cvt_pk_bf16_f32 v5, v6, v7
	v_lshlrev_b32_e32 v6, 16, v46
	v_and_b32_e32 v7, 0xffff0000, v46
	s_waitcnt lgkmcnt(0)
	v_pk_mul_f32 v[0:1], v[0:1], v[6:7]
	s_nop 0
	v_cvt_pk_bf16_f32 v6, v0, v1
	v_lshlrev_b32_e32 v0, 16, v47
	v_and_b32_e32 v1, 0xffff0000, v47
	v_pk_mul_f32 v[0:1], v[2:3], v[0:1]
	s_nop 0
	v_cvt_pk_bf16_f32 v7, v0, v1
	v_lshl_add_u64 v[0:1], v[8:9], 0, v[48:49]
	v_lshl_add_u64 v[0:1], v[0:1], 0, s[30:31]
	global_store_dwordx4 v[0:1], v[4:7], off nt
	s_barrier
	s_cbranch_scc0 .LBB0_175
